# attention inner loop: exp/index temps renamed off the ones-vector regs v5-v7 (to free v240-242), drops 96 v_mov re-materialisations per loop body; on v91
# baseline (speedup 1.0000x reference)
.LBB0_328:
	global_load_dwordx4 v[132:135], v[210:211], off
	global_load_dwordx4 v[140:143], v[210:211], off offset:1024
	global_load_dwordx4 v[144:147], v[208:209], off
	global_load_dwordx4 v[148:151], v[208:209], off offset:1024
	v_lshl_add_u64 v[2:3], v[208:209], 0, s[52:53]
	v_lshl_add_u64 v[244:245], v[210:211], 0, s[52:53]
	v_mov_b64_e32 v[208:209], v[2:3]
	v_mov_b64_e32 v[210:211], v[244:245]

; __device__ __forceinline__ void attn_unit(LAS unsigned char* lds, const bf16* PROJ, bf16* YMIX, float* ssq, const float* relb, const float* gqn, const float* gkn,
;                                           int b, int h, int c0, int wave, int lane_in, int tid_in) {
;     ...
;     typedef short v4i16_t __attribute__((ext_vector_type(4)));
;     for (int jp = j0 >> 1; jp < 8; jp += 2) {
;         __syncthreads();
.LBB0_331:
	s_add_i32 s13, 0, 0x12000
	v_mov_b32_e32 v0, s13
	s_waitcnt lgkmcnt(0)
	s_barrier
	v_mov_b32_e32 v5, v4
	v_mov_b32_e32 v6, v4
	v_mov_b32_e32 v7, v4
	ds_read_b32 v152, v0
	ds_read_b128 v[172:175], v237
	ds_read_b128 v[176:179], v237 offset:64
	ds_read_b128 v[180:183], v237 offset:2304
	ds_read_b128 v[184:187], v237 offset:2368
	ds_read_b64_tr_b16 v[156:157], v238 offset:9216
	ds_read_b64_tr_b16 v[158:159], v239 offset:9216
	ds_read_b64_tr_b16 v[160:161], v238 offset:9248
	ds_read_b64_tr_b16 v[164:165], v238 offset:9280
	ds_read_b64_tr_b16 v[168:169], v238 offset:9312
	ds_read_b64_tr_b16 v[162:163], v239 offset:9248
	ds_read_b64_tr_b16 v[166:167], v239 offset:9280
	ds_read_b64_tr_b16 v[170:171], v239 offset:9312
	s_lshl_b32 s20, s18, 1
	s_sub_i32 s21, s20, s85
	s_cmp_lt_u32 s21, 9
	s_waitcnt lgkmcnt(12)
	v_mov_b32_e32 v153, v152
	v_mov_b32_e32 v154, v152
	s_cselect_b64 s[66:67], -1, 0
	s_cmp_gt_u32 s21, 8
	v_mov_b32_e32 v155, v152
	s_cbranch_scc1 .LBB0_337
	s_cmp_lt_u32 s21, 6
	s_mov_b64 s[4:5], -1
	s_cbranch_scc1 .LBB0_334
	v_lshl_add_u32 v0, s21, 6, v233
	v_max_i32_e32 v188, 0xffffffef, v0
	v_max_i32_e32 v2, 0, v0
	v_lshl_add_u32 v193, v188, 2, s13
	v_max_i32_e32 v188, 0xffffffee, v0
	v_lshl_add_u32 v2, v2, 2, s13
	v_max_i32_e32 v3, -1, v0
	v_max_i32_e32 v240, -2, v0
	v_max_i32_e32 v241, -3, v0
	v_max_i32_e32 v242, -16, v0
	v_lshl_add_u32 v194, v188, 2, s13
	v_max_i32_e32 v0, 0xffffffed, v0
	v_lshl_add_u32 v3, v3, 2, s13
	v_lshl_add_u32 v240, v240, 2, s13
	v_lshl_add_u32 v241, v241, 2, s13
	v_lshl_add_u32 v242, v242, 2, s13
	v_lshl_add_u32 v0, v0, 2, s13
	ds_read_b32 v188, v2
	ds_read_b32 v189, v3 offset:4
	ds_read_b32 v190, v240 offset:8
	ds_read_b32 v191, v241 offset:12
	ds_read_b32 v192, v242 offset:64
	ds_read_b32 v193, v193 offset:68
	ds_read_b32 v194, v194 offset:72
	ds_read_b32 v195, v0 offset:76
	s_waitcnt lgkmcnt(4)
	v_mfma_f32_16x16x32_bf16 v[188:191], v[172:175], v[64:67], v[188:191]
	s_mov_b64 s[4:5], 0
	s_waitcnt lgkmcnt(0)
	v_mfma_f32_16x16x32_bf16 v[192:195], v[180:183], v[64:67], v[192:195]
	s_nop 0
	v_mfma_f32_16x16x32_bf16 v[188:191], v[176:179], v[68:71], v[188:191]
	v_mfma_f32_16x16x32_bf16 v[192:195], v[184:187], v[68:71], v[192:195]

.LBB0_336:
	s_nop 7
	v_exp_f32_e32 v2, v192
	v_exp_f32_e32 v240, v193
	v_exp_f32_e32 v241, v190
	v_exp_f32_e32 v242, v191
	v_exp_f32_e32 v0, v188
	v_exp_f32_e32 v3, v189
	v_exp_f32_e32 v191, v194
	v_exp_f32_e32 v192, v195
	v_cvt_pk_bf16_f32 v189, v241, v242
	v_cvt_pk_bf16_f32 v190, v2, v240
	v_cvt_pk_bf16_f32 v188, v0, v3
	v_cvt_pk_bf16_f32 v191, v191, v192
	s_waitcnt lgkmcnt(6)
	s_nop 0
	v_mfma_f32_16x16x32_bf16 v[120:123], v[156:159], v[188:191], v[120:123]
	s_waitcnt lgkmcnt(2)
	v_mfma_f32_16x16x32_bf16 v[108:111], v[160:163], v[188:191], v[108:111]
	s_waitcnt lgkmcnt(1)
	v_mfma_f32_16x16x32_bf16 v[104:107], v[164:167], v[188:191], v[104:107]
	s_waitcnt lgkmcnt(0)
	v_mfma_f32_16x16x32_bf16 v[100:103], v[168:171], v[188:191], v[100:103]
	v_mfma_f32_16x16x32_bf16 v[136:139], v[4:7], v[188:191], v[136:139]
.LBB0_337:
	s_add_i32 s14, s21, -2
	s_cmp_lt_u32 s14, 9
	s_cselect_b64 s[68:69], -1, 0
	s_cmp_gt_u32 s14, 8
	s_cbranch_scc1 .LBB0_343
	s_cmp_lt_u32 s14, 6
	s_mov_b64 s[4:5], -1
	s_cbranch_scc1 .LBB0_340
	v_lshl_add_u32 v0, s14, 6, v233
	v_max_i32_e32 v188, 0xffffffef, v0
	v_max_i32_e32 v2, 0, v0
	v_lshl_add_u32 v193, v188, 2, s13
	v_max_i32_e32 v188, 0xffffffee, v0
	v_lshl_add_u32 v2, v2, 2, s13
	v_max_i32_e32 v3, -1, v0
	v_max_i32_e32 v240, -2, v0
	v_max_i32_e32 v241, -3, v0
	v_max_i32_e32 v242, -16, v0
	v_lshl_add_u32 v194, v188, 2, s13
	v_max_i32_e32 v0, 0xffffffed, v0
	v_lshl_add_u32 v3, v3, 2, s13
	v_lshl_add_u32 v240, v240, 2, s13
	v_lshl_add_u32 v241, v241, 2, s13
	v_lshl_add_u32 v242, v242, 2, s13
	v_lshl_add_u32 v0, v0, 2, s13
	ds_read_b32 v188, v2
	ds_read_b32 v189, v3 offset:4
	ds_read_b32 v190, v240 offset:8
	ds_read_b32 v191, v241 offset:12
	ds_read_b32 v192, v242 offset:64
	ds_read_b32 v193, v193 offset:68
	ds_read_b32 v194, v194 offset:72
	ds_read_b32 v195, v0 offset:76
	s_waitcnt lgkmcnt(4)
	v_mfma_f32_16x16x32_bf16 v[188:191], v[172:175], v[76:79], v[188:191]
	s_mov_b64 s[4:5], 0
	s_waitcnt lgkmcnt(0)
	v_mfma_f32_16x16x32_bf16 v[192:195], v[180:183], v[76:79], v[192:195]
	s_nop 0
	v_mfma_f32_16x16x32_bf16 v[188:191], v[176:179], v[80:83], v[188:191]
	v_mfma_f32_16x16x32_bf16 v[192:195], v[184:187], v[80:83], v[192:195]

.LBB0_342:
	s_nop 7
	v_exp_f32_e32 v2, v192
	v_exp_f32_e32 v240, v193
	v_exp_f32_e32 v241, v190
	v_exp_f32_e32 v242, v191
	v_exp_f32_e32 v0, v188
	v_exp_f32_e32 v3, v189
	v_exp_f32_e32 v191, v194
	v_exp_f32_e32 v192, v195
	v_cvt_pk_bf16_f32 v189, v241, v242
	v_cvt_pk_bf16_f32 v190, v2, v240
	v_cvt_pk_bf16_f32 v188, v0, v3
	v_cvt_pk_bf16_f32 v191, v191, v192
	s_waitcnt lgkmcnt(6)
	s_nop 0
	v_mfma_f32_16x16x32_bf16 v[60:63], v[156:159], v[188:191], v[60:63]
	s_waitcnt lgkmcnt(2)
	v_mfma_f32_16x16x32_bf16 v[56:59], v[160:163], v[188:191], v[56:59]
	s_waitcnt lgkmcnt(1)
	v_mfma_f32_16x16x32_bf16 v[52:55], v[164:167], v[188:191], v[52:55]
	s_waitcnt lgkmcnt(0)
	v_mfma_f32_16x16x32_bf16 v[48:51], v[168:171], v[188:191], v[48:51]
	v_mfma_f32_16x16x32_bf16 v[72:75], v[4:7], v[188:191], v[72:75]
.LBB0_343:
	s_add_i32 s15, s21, -4
	s_cmp_lt_u32 s15, 9
	s_cselect_b64 s[70:71], -1, 0
	s_cmp_gt_u32 s15, 8
	s_cbranch_scc1 .LBB0_349
	s_cmp_lt_u32 s15, 6
	s_mov_b64 s[4:5], -1
	s_cbranch_scc1 .LBB0_346
	v_lshl_add_u32 v0, s15, 6, v233
	v_max_i32_e32 v188, 0xffffffef, v0
	v_max_i32_e32 v2, 0, v0
	v_lshl_add_u32 v193, v188, 2, s13
	v_max_i32_e32 v188, 0xffffffee, v0
	v_lshl_add_u32 v2, v2, 2, s13
	v_max_i32_e32 v3, -1, v0
	v_max_i32_e32 v240, -2, v0
	v_max_i32_e32 v241, -3, v0
	v_max_i32_e32 v242, -16, v0
	v_lshl_add_u32 v194, v188, 2, s13
	v_max_i32_e32 v0, 0xffffffed, v0
	v_lshl_add_u32 v3, v3, 2, s13
	v_lshl_add_u32 v240, v240, 2, s13
	v_lshl_add_u32 v241, v241, 2, s13
	v_lshl_add_u32 v242, v242, 2, s13
	v_lshl_add_u32 v0, v0, 2, s13
	ds_read_b32 v188, v2
	ds_read_b32 v189, v3 offset:4
	ds_read_b32 v190, v240 offset:8
	ds_read_b32 v191, v241 offset:12
	ds_read_b32 v192, v242 offset:64
	ds_read_b32 v193, v193 offset:68
	ds_read_b32 v194, v194 offset:72
	ds_read_b32 v195, v0 offset:76
	s_waitcnt lgkmcnt(4)
	v_mfma_f32_16x16x32_bf16 v[188:191], v[172:175], v[84:87], v[188:191]
	s_mov_b64 s[4:5], 0
	s_waitcnt lgkmcnt(0)
	v_mfma_f32_16x16x32_bf16 v[192:195], v[180:183], v[84:87], v[192:195]
	s_nop 0
	v_mfma_f32_16x16x32_bf16 v[188:191], v[176:179], v[88:91], v[188:191]
	v_mfma_f32_16x16x32_bf16 v[192:195], v[184:187], v[88:91], v[192:195]

.LBB0_348:
	s_nop 7
	v_exp_f32_e32 v2, v192
	v_exp_f32_e32 v240, v193
	v_exp_f32_e32 v241, v190
	v_exp_f32_e32 v242, v191
	v_exp_f32_e32 v0, v188
	v_exp_f32_e32 v3, v189
	v_exp_f32_e32 v191, v194
	v_exp_f32_e32 v192, v195
	v_cvt_pk_bf16_f32 v189, v241, v242
	v_cvt_pk_bf16_f32 v190, v2, v240
	v_cvt_pk_bf16_f32 v188, v0, v3
	v_cvt_pk_bf16_f32 v191, v191, v192
	s_waitcnt lgkmcnt(6)
	s_nop 0
	v_mfma_f32_16x16x32_bf16 v[40:43], v[156:159], v[188:191], v[40:43]
	s_waitcnt lgkmcnt(2)
	v_mfma_f32_16x16x32_bf16 v[36:39], v[160:163], v[188:191], v[36:39]
	s_waitcnt lgkmcnt(1)
	v_mfma_f32_16x16x32_bf16 v[32:35], v[164:167], v[188:191], v[32:35]
	s_waitcnt lgkmcnt(0)
	v_mfma_f32_16x16x32_bf16 v[28:31], v[168:171], v[188:191], v[28:31]
	v_mfma_f32_16x16x32_bf16 v[44:47], v[4:7], v[188:191], v[44:47]
.LBB0_349:
	s_add_i32 s17, s21, -6
	s_cmp_lt_u32 s17, 9
	s_cselect_b64 s[72:73], -1, 0
	s_cmp_gt_u32 s17, 8
	s_cbranch_scc1 .LBB0_355
	s_cmp_lt_u32 s17, 6
	s_mov_b64 s[4:5], -1
	s_cbranch_scc1 .LBB0_352
	v_lshl_add_u32 v0, s17, 6, v233
	v_max_i32_e32 v188, 0xffffffef, v0
	v_max_i32_e32 v2, 0, v0
	v_lshl_add_u32 v193, v188, 2, s13
	v_max_i32_e32 v188, 0xffffffee, v0
	v_lshl_add_u32 v2, v2, 2, s13
	v_max_i32_e32 v3, -1, v0
	v_max_i32_e32 v240, -2, v0
	v_max_i32_e32 v241, -3, v0
	v_max_i32_e32 v242, -16, v0
	v_lshl_add_u32 v194, v188, 2, s13
	v_max_i32_e32 v0, 0xffffffed, v0
	v_lshl_add_u32 v3, v3, 2, s13
	v_lshl_add_u32 v240, v240, 2, s13
	v_lshl_add_u32 v241, v241, 2, s13
	v_lshl_add_u32 v242, v242, 2, s13
	v_lshl_add_u32 v0, v0, 2, s13
	ds_read_b32 v188, v2
	ds_read_b32 v189, v3 offset:4
	ds_read_b32 v190, v240 offset:8
	ds_read_b32 v191, v241 offset:12
	ds_read_b32 v192, v242 offset:64
	ds_read_b32 v193, v193 offset:68
	ds_read_b32 v194, v194 offset:72
	ds_read_b32 v195, v0 offset:76
	s_waitcnt lgkmcnt(4)
	v_mfma_f32_16x16x32_bf16 v[188:191], v[172:175], v[92:95], v[188:191]
	s_mov_b64 s[4:5], 0
	s_waitcnt lgkmcnt(0)
	v_mfma_f32_16x16x32_bf16 v[192:195], v[180:183], v[92:95], v[192:195]
	s_nop 0
	v_mfma_f32_16x16x32_bf16 v[188:191], v[176:179], v[96:99], v[188:191]
	v_mfma_f32_16x16x32_bf16 v[192:195], v[184:187], v[96:99], v[192:195]

.LBB0_354:
	s_nop 7
	v_exp_f32_e32 v2, v192
	v_exp_f32_e32 v240, v193
	v_exp_f32_e32 v241, v190
	v_exp_f32_e32 v242, v191
	v_exp_f32_e32 v0, v188
	v_exp_f32_e32 v3, v189
	s_waitcnt lgkmcnt(11)
	v_exp_f32_e32 v175, v194
	s_waitcnt lgkmcnt(10)
	v_exp_f32_e32 v176, v195
	v_cvt_pk_bf16_f32 v173, v241, v242
	v_cvt_pk_bf16_f32 v174, v2, v240
	v_cvt_pk_bf16_f32 v172, v0, v3
	v_cvt_pk_bf16_f32 v175, v175, v176
	s_waitcnt lgkmcnt(6)
	s_nop 0
	v_mfma_f32_16x16x32_bf16 v[20:23], v[156:159], v[172:175], v[20:23]
	s_waitcnt lgkmcnt(2)
	v_mfma_f32_16x16x32_bf16 v[16:19], v[160:163], v[172:175], v[16:19]
	s_waitcnt lgkmcnt(1)
	v_mfma_f32_16x16x32_bf16 v[12:15], v[164:167], v[172:175], v[12:15]
	s_waitcnt lgkmcnt(0)
	v_mfma_f32_16x16x32_bf16 v[8:11], v[168:171], v[172:175], v[8:11]
	v_mfma_f32_16x16x32_bf16 v[24:27], v[4:7], v[172:175], v[24:27]

.LBB0_359:
	s_cmp_lt_u32 s21, 6
	s_mov_b64 s[66:67], -1
	s_cbranch_scc1 .LBB0_361
	v_lshl_add_u32 v0, s21, 6, v234
	v_max_i32_e32 v188, 0xffffffef, v0
	v_max_i32_e32 v2, 0, v0
	v_lshl_add_u32 v193, v188, 2, s13
	v_max_i32_e32 v188, 0xffffffee, v0
	v_lshl_add_u32 v2, v2, 2, s13
	v_max_i32_e32 v3, -1, v0
	v_max_i32_e32 v240, -2, v0
	v_max_i32_e32 v241, -3, v0
	v_max_i32_e32 v242, -16, v0
	v_lshl_add_u32 v194, v188, 2, s13
	v_max_i32_e32 v0, 0xffffffed, v0
	v_lshl_add_u32 v3, v3, 2, s13
	v_lshl_add_u32 v240, v240, 2, s13
	v_lshl_add_u32 v241, v241, 2, s13
	v_lshl_add_u32 v242, v242, 2, s13
	v_lshl_add_u32 v0, v0, 2, s13
	ds_read_b32 v188, v2
	ds_read_b32 v189, v3 offset:4
	ds_read_b32 v190, v240 offset:8
	ds_read_b32 v191, v241 offset:12
	ds_read_b32 v192, v242 offset:64
	ds_read_b32 v193, v193 offset:68
	ds_read_b32 v194, v194 offset:72
	ds_read_b32 v195, v0 offset:76
	s_waitcnt lgkmcnt(4)
	v_mfma_f32_16x16x32_bf16 v[188:191], v[172:175], v[64:67], v[188:191]
	s_mov_b64 s[66:67], 0
	s_waitcnt lgkmcnt(0)
	v_mfma_f32_16x16x32_bf16 v[192:195], v[180:183], v[64:67], v[192:195]
	s_nop 0
	v_mfma_f32_16x16x32_bf16 v[188:191], v[176:179], v[68:71], v[188:191]
	v_mfma_f32_16x16x32_bf16 v[192:195], v[184:187], v[68:71], v[192:195]

.LBB0_363:
	s_nop 7
	v_exp_f32_e32 v2, v192
	v_exp_f32_e32 v240, v193
	v_exp_f32_e32 v241, v190
	v_exp_f32_e32 v242, v191
	v_exp_f32_e32 v0, v188
	v_exp_f32_e32 v3, v189
	v_exp_f32_e32 v191, v194
	v_exp_f32_e32 v192, v195
	v_cvt_pk_bf16_f32 v189, v241, v242
	v_cvt_pk_bf16_f32 v190, v2, v240
	v_cvt_pk_bf16_f32 v188, v0, v3
	v_cvt_pk_bf16_f32 v191, v191, v192
	s_waitcnt lgkmcnt(3)
	s_nop 0
	v_mfma_f32_16x16x32_bf16 v[120:123], v[160:163], v[188:191], v[120:123]
	s_waitcnt lgkmcnt(2)
	v_mfma_f32_16x16x32_bf16 v[108:111], v[156:159], v[188:191], v[108:111]
	s_waitcnt lgkmcnt(1)
	v_mfma_f32_16x16x32_bf16 v[104:107], v[164:167], v[188:191], v[104:107]
	s_waitcnt lgkmcnt(0)
	v_mfma_f32_16x16x32_bf16 v[100:103], v[168:171], v[188:191], v[100:103]
	v_mfma_f32_16x16x32_bf16 v[136:139], v[4:7], v[188:191], v[136:139]
	s_andn2_b64 vcc, exec, s[68:69]
	s_cbranch_vccnz .LBB0_357
.LBB0_364:
	s_cmp_lt_u32 s14, 6
	s_mov_b64 s[66:67], -1
	s_cbranch_scc1 .LBB0_366
	v_lshl_add_u32 v0, s14, 6, v234
	v_max_i32_e32 v188, 0xffffffef, v0
	v_max_i32_e32 v2, 0, v0
	v_lshl_add_u32 v193, v188, 2, s13
	v_max_i32_e32 v188, 0xffffffee, v0
	v_lshl_add_u32 v2, v2, 2, s13
	v_max_i32_e32 v3, -1, v0
	v_max_i32_e32 v240, -2, v0
	v_max_i32_e32 v241, -3, v0
	v_max_i32_e32 v242, -16, v0
	v_lshl_add_u32 v194, v188, 2, s13
	v_max_i32_e32 v0, 0xffffffed, v0
	v_lshl_add_u32 v3, v3, 2, s13
	v_lshl_add_u32 v240, v240, 2, s13
	v_lshl_add_u32 v241, v241, 2, s13
	v_lshl_add_u32 v242, v242, 2, s13
	v_lshl_add_u32 v0, v0, 2, s13
	ds_read_b32 v188, v2
	ds_read_b32 v189, v3 offset:4
	ds_read_b32 v190, v240 offset:8
	ds_read_b32 v191, v241 offset:12
	ds_read_b32 v192, v242 offset:64
	ds_read_b32 v193, v193 offset:68
	ds_read_b32 v194, v194 offset:72
	ds_read_b32 v195, v0 offset:76
	s_waitcnt lgkmcnt(4)
	v_mfma_f32_16x16x32_bf16 v[188:191], v[172:175], v[76:79], v[188:191]
	s_mov_b64 s[66:67], 0
	s_waitcnt lgkmcnt(0)
	v_mfma_f32_16x16x32_bf16 v[192:195], v[180:183], v[76:79], v[192:195]
	s_nop 0
	v_mfma_f32_16x16x32_bf16 v[188:191], v[176:179], v[80:83], v[188:191]
	v_mfma_f32_16x16x32_bf16 v[192:195], v[184:187], v[80:83], v[192:195]

.LBB0_368:
	s_nop 7
	v_exp_f32_e32 v2, v192
	v_exp_f32_e32 v240, v193
	v_exp_f32_e32 v241, v190
	v_exp_f32_e32 v242, v191
	v_exp_f32_e32 v0, v188
	v_exp_f32_e32 v3, v189
	v_exp_f32_e32 v191, v194
	v_exp_f32_e32 v192, v195
	v_cvt_pk_bf16_f32 v189, v241, v242
	v_cvt_pk_bf16_f32 v190, v2, v240
	v_cvt_pk_bf16_f32 v188, v0, v3
	v_cvt_pk_bf16_f32 v191, v191, v192
	s_waitcnt lgkmcnt(3)
	s_nop 0
	v_mfma_f32_16x16x32_bf16 v[60:63], v[160:163], v[188:191], v[60:63]
	s_waitcnt lgkmcnt(2)
	v_mfma_f32_16x16x32_bf16 v[56:59], v[156:159], v[188:191], v[56:59]
	s_waitcnt lgkmcnt(1)
	v_mfma_f32_16x16x32_bf16 v[52:55], v[164:167], v[188:191], v[52:55]
	s_waitcnt lgkmcnt(0)
	v_mfma_f32_16x16x32_bf16 v[48:51], v[168:171], v[188:191], v[48:51]
	v_mfma_f32_16x16x32_bf16 v[72:75], v[4:7], v[188:191], v[72:75]
	s_andn2_b64 vcc, exec, s[70:71]
	s_cbranch_vccnz .LBB0_358
.LBB0_369:
	s_cmp_lt_u32 s15, 6
	s_mov_b64 s[66:67], -1
	s_cbranch_scc1 .LBB0_371
	v_lshl_add_u32 v0, s15, 6, v234
	v_max_i32_e32 v188, 0xffffffef, v0
	v_max_i32_e32 v2, 0, v0
	v_lshl_add_u32 v193, v188, 2, s13
	v_max_i32_e32 v188, 0xffffffee, v0
	v_lshl_add_u32 v2, v2, 2, s13
	v_max_i32_e32 v3, -1, v0
	v_max_i32_e32 v240, -2, v0
	v_max_i32_e32 v241, -3, v0
	v_max_i32_e32 v242, -16, v0
	v_lshl_add_u32 v194, v188, 2, s13
	v_max_i32_e32 v0, 0xffffffed, v0
	v_lshl_add_u32 v3, v3, 2, s13
	v_lshl_add_u32 v240, v240, 2, s13
	v_lshl_add_u32 v241, v241, 2, s13
	v_lshl_add_u32 v242, v242, 2, s13
	v_lshl_add_u32 v0, v0, 2, s13
	ds_read_b32 v188, v2
	ds_read_b32 v189, v3 offset:4
	ds_read_b32 v190, v240 offset:8
	ds_read_b32 v191, v241 offset:12
	ds_read_b32 v192, v242 offset:64
	ds_read_b32 v193, v193 offset:68
	ds_read_b32 v194, v194 offset:72
	ds_read_b32 v195, v0 offset:76
	s_waitcnt lgkmcnt(4)
	v_mfma_f32_16x16x32_bf16 v[188:191], v[172:175], v[84:87], v[188:191]
	s_mov_b64 s[66:67], 0
	s_waitcnt lgkmcnt(0)
	v_mfma_f32_16x16x32_bf16 v[192:195], v[180:183], v[84:87], v[192:195]
	s_nop 0
	v_mfma_f32_16x16x32_bf16 v[188:191], v[176:179], v[88:91], v[188:191]
	v_mfma_f32_16x16x32_bf16 v[192:195], v[184:187], v[88:91], v[192:195]

.LBB0_373:
	s_nop 7
	v_exp_f32_e32 v2, v192
	v_exp_f32_e32 v240, v193
	v_exp_f32_e32 v241, v190
	v_exp_f32_e32 v242, v191
	v_exp_f32_e32 v0, v188
	v_exp_f32_e32 v3, v189
	v_exp_f32_e32 v191, v194
	v_exp_f32_e32 v192, v195
	v_cvt_pk_bf16_f32 v189, v241, v242
	v_cvt_pk_bf16_f32 v190, v2, v240
	v_cvt_pk_bf16_f32 v188, v0, v3
	v_cvt_pk_bf16_f32 v191, v191, v192
	s_waitcnt lgkmcnt(3)
	s_nop 0
	v_mfma_f32_16x16x32_bf16 v[40:43], v[160:163], v[188:191], v[40:43]
	s_waitcnt lgkmcnt(2)
	v_mfma_f32_16x16x32_bf16 v[36:39], v[156:159], v[188:191], v[36:39]
	s_waitcnt lgkmcnt(1)
	v_mfma_f32_16x16x32_bf16 v[32:35], v[164:167], v[188:191], v[32:35]
	s_waitcnt lgkmcnt(0)
	v_mfma_f32_16x16x32_bf16 v[28:31], v[168:171], v[188:191], v[28:31]
	v_mfma_f32_16x16x32_bf16 v[44:47], v[4:7], v[188:191], v[44:47]
	s_andn2_b64 vcc, exec, s[72:73]
	s_cbranch_vccnz .LBB0_379
.LBB0_374:
	s_cmp_lt_u32 s17, 6
	s_mov_b64 s[66:67], -1
	s_cbranch_scc1 .LBB0_376
	v_lshl_add_u32 v0, s17, 6, v234
	v_max_i32_e32 v188, 0xffffffef, v0
	v_max_i32_e32 v2, 0, v0
	v_lshl_add_u32 v193, v188, 2, s13
	v_max_i32_e32 v188, 0xffffffee, v0
	v_lshl_add_u32 v2, v2, 2, s13
	v_max_i32_e32 v3, -1, v0
	v_max_i32_e32 v240, -2, v0
	v_max_i32_e32 v241, -3, v0
	v_max_i32_e32 v242, -16, v0
	v_lshl_add_u32 v194, v188, 2, s13
	v_max_i32_e32 v0, 0xffffffed, v0
	v_lshl_add_u32 v3, v3, 2, s13
	v_lshl_add_u32 v240, v240, 2, s13
	v_lshl_add_u32 v241, v241, 2, s13
	v_lshl_add_u32 v242, v242, 2, s13
	v_lshl_add_u32 v0, v0, 2, s13
	ds_read_b32 v188, v2
	ds_read_b32 v189, v3 offset:4
	ds_read_b32 v190, v240 offset:8
	ds_read_b32 v191, v241 offset:12
	ds_read_b32 v192, v242 offset:64
	ds_read_b32 v193, v193 offset:68
	ds_read_b32 v194, v194 offset:72
	ds_read_b32 v195, v0 offset:76
	s_waitcnt lgkmcnt(4)
	v_mfma_f32_16x16x32_bf16 v[188:191], v[172:175], v[92:95], v[188:191]
	s_mov_b64 s[66:67], 0
	s_waitcnt lgkmcnt(0)
	v_mfma_f32_16x16x32_bf16 v[192:195], v[180:183], v[92:95], v[192:195]
	s_nop 0
	v_mfma_f32_16x16x32_bf16 v[188:191], v[176:179], v[96:99], v[188:191]
	v_mfma_f32_16x16x32_bf16 v[192:195], v[184:187], v[96:99], v[192:195]

.LBB0_378:
	s_nop 7
	v_exp_f32_e32 v2, v192
	v_exp_f32_e32 v240, v193
	v_exp_f32_e32 v241, v190
	v_exp_f32_e32 v242, v191
	v_exp_f32_e32 v0, v188
	v_exp_f32_e32 v3, v189
	s_waitcnt lgkmcnt(11)
	v_exp_f32_e32 v175, v194
	s_waitcnt lgkmcnt(10)
	v_exp_f32_e32 v176, v195
	v_cvt_pk_bf16_f32 v173, v241, v242
	v_cvt_pk_bf16_f32 v174, v2, v240
	v_cvt_pk_bf16_f32 v172, v0, v3
	v_cvt_pk_bf16_f32 v175, v175, v176
	s_waitcnt lgkmcnt(3)
	s_nop 0
	v_mfma_f32_16x16x32_bf16 v[20:23], v[160:163], v[172:175], v[20:23]
	s_waitcnt lgkmcnt(2)
	v_mfma_f32_16x16x32_bf16 v[16:19], v[156:159], v[172:175], v[16:19]
	s_waitcnt lgkmcnt(1)
	v_mfma_f32_16x16x32_bf16 v[12:15], v[164:167], v[172:175], v[12:15]
	s_waitcnt lgkmcnt(0)
	v_mfma_f32_16x16x32_bf16 v[8:11], v[168:171], v[172:175], v[8:11]
	v_mfma_f32_16x16x32_bf16 v[24:27], v[4:7], v[172:175], v[24:27]
.LBB0_379:
	s_waitcnt lgkmcnt(11)
	ds_read_b128 v[172:175], v237 offset:18432
	s_waitcnt lgkmcnt(11)
	ds_read_b128 v[176:179], v237 offset:18496
	s_waitcnt lgkmcnt(11)
	ds_read_b128 v[180:183], v237 offset:20736
	s_waitcnt lgkmcnt(11)
	ds_read_b128 v[184:187], v237 offset:20800
	s_waitcnt lgkmcnt(11)
	ds_read_b64_tr_b16 v[160:161], v238 offset:27648
	s_waitcnt lgkmcnt(11)
	ds_read_b64_tr_b16 v[156:157], v238 offset:27680
	s_waitcnt lgkmcnt(11)
	ds_read_b64_tr_b16 v[164:165], v238 offset:27712
	s_waitcnt lgkmcnt(11)
	ds_read_b64_tr_b16 v[168:169], v238 offset:27744
	s_waitcnt lgkmcnt(11)
	ds_read_b64_tr_b16 v[162:163], v239 offset:27648
	s_waitcnt lgkmcnt(11)
	ds_read_b64_tr_b16 v[158:159], v239 offset:27680
	s_waitcnt lgkmcnt(11)
	ds_read_b64_tr_b16 v[166:167], v239 offset:27712
	s_waitcnt lgkmcnt(11)
	ds_read_b64_tr_b16 v[170:171], v239 offset:27744
	s_or_b32 s24, s20, 1
	s_sub_i32 s14, s24, s85
	s_cmp_lt_u32 s14, 9
	s_cselect_b64 s[66:67], -1, 0
	s_cmp_gt_u32 s14, 8
	s_cbranch_scc1 .LBB0_385
	s_cmp_lt_u32 s14, 6
	s_mov_b64 s[68:69], -1
	s_cbranch_scc1 .LBB0_382
	v_lshl_add_u32 v0, s14, 6, v233
	v_max_i32_e32 v188, 0xffffffef, v0
	v_max_i32_e32 v2, 0, v0
	v_lshl_add_u32 v193, v188, 2, s13
	v_max_i32_e32 v188, 0xffffffee, v0
	v_lshl_add_u32 v2, v2, 2, s13
	v_max_i32_e32 v3, -1, v0
	v_max_i32_e32 v240, -2, v0
	v_max_i32_e32 v241, -3, v0
	v_max_i32_e32 v242, -16, v0
	v_lshl_add_u32 v194, v188, 2, s13
	v_max_i32_e32 v0, 0xffffffed, v0
	v_lshl_add_u32 v3, v3, 2, s13
	v_lshl_add_u32 v240, v240, 2, s13
	v_lshl_add_u32 v241, v241, 2, s13
	v_lshl_add_u32 v242, v242, 2, s13
	v_lshl_add_u32 v0, v0, 2, s13
	ds_read_b32 v188, v2
	ds_read_b32 v189, v3 offset:4
	ds_read_b32 v190, v240 offset:8
	ds_read_b32 v191, v241 offset:12
	ds_read_b32 v192, v242 offset:64
	ds_read_b32 v193, v193 offset:68
	ds_read_b32 v194, v194 offset:72
	ds_read_b32 v195, v0 offset:76
	s_waitcnt lgkmcnt(4)
	v_mfma_f32_16x16x32_bf16 v[188:191], v[172:175], v[64:67], v[188:191]
	s_mov_b64 s[68:69], 0
	s_waitcnt lgkmcnt(0)
	v_mfma_f32_16x16x32_bf16 v[192:195], v[180:183], v[64:67], v[192:195]
	s_nop 0
	v_mfma_f32_16x16x32_bf16 v[188:191], v[176:179], v[68:71], v[188:191]
	v_mfma_f32_16x16x32_bf16 v[192:195], v[184:187], v[68:71], v[192:195]

.LBB0_384:
	s_nop 7
	v_exp_f32_e32 v2, v192
	v_exp_f32_e32 v240, v193
	v_exp_f32_e32 v241, v190
	v_exp_f32_e32 v242, v191
	v_exp_f32_e32 v0, v188
	v_exp_f32_e32 v3, v189
	v_exp_f32_e32 v191, v194
	v_exp_f32_e32 v192, v195
	v_cvt_pk_bf16_f32 v189, v241, v242
	v_cvt_pk_bf16_f32 v190, v2, v240
	v_cvt_pk_bf16_f32 v188, v0, v3
	v_cvt_pk_bf16_f32 v191, v191, v192
	s_waitcnt lgkmcnt(3)
	s_nop 0
	v_mfma_f32_16x16x32_bf16 v[120:123], v[160:163], v[188:191], v[120:123]
	s_waitcnt lgkmcnt(2)
	v_mfma_f32_16x16x32_bf16 v[108:111], v[156:159], v[188:191], v[108:111]
	s_waitcnt lgkmcnt(1)
	v_mfma_f32_16x16x32_bf16 v[104:107], v[164:167], v[188:191], v[104:107]
	s_waitcnt lgkmcnt(0)
	v_mfma_f32_16x16x32_bf16 v[100:103], v[168:171], v[188:191], v[100:103]
	v_mfma_f32_16x16x32_bf16 v[136:139], v[4:7], v[188:191], v[136:139]
.LBB0_385:
	s_sub_i32 s15, s24, s19
	s_cmp_lt_u32 s15, 9
	s_cselect_b64 s[68:69], -1, 0
	s_cmp_gt_u32 s15, 8
	s_cbranch_scc1 .LBB0_391
	s_cmp_lt_u32 s15, 6
	s_mov_b64 s[70:71], -1
	s_cbranch_scc1 .LBB0_388
	v_lshl_add_u32 v0, s15, 6, v233
	v_max_i32_e32 v188, 0xffffffef, v0
	v_max_i32_e32 v2, 0, v0
	v_lshl_add_u32 v193, v188, 2, s13
	v_max_i32_e32 v188, 0xffffffee, v0
	v_lshl_add_u32 v2, v2, 2, s13
	v_max_i32_e32 v3, -1, v0
	v_max_i32_e32 v240, -2, v0
	v_max_i32_e32 v241, -3, v0
	v_max_i32_e32 v242, -16, v0
	v_lshl_add_u32 v194, v188, 2, s13
	v_max_i32_e32 v0, 0xffffffed, v0
	v_lshl_add_u32 v3, v3, 2, s13
	v_lshl_add_u32 v240, v240, 2, s13
	v_lshl_add_u32 v241, v241, 2, s13
	v_lshl_add_u32 v242, v242, 2, s13
	v_lshl_add_u32 v0, v0, 2, s13
	ds_read_b32 v188, v2
	ds_read_b32 v189, v3 offset:4
	ds_read_b32 v190, v240 offset:8
	ds_read_b32 v191, v241 offset:12
	ds_read_b32 v192, v242 offset:64
	ds_read_b32 v193, v193 offset:68
	ds_read_b32 v194, v194 offset:72
	ds_read_b32 v195, v0 offset:76
	s_waitcnt lgkmcnt(4)
	v_mfma_f32_16x16x32_bf16 v[188:191], v[172:175], v[76:79], v[188:191]
	s_mov_b64 s[70:71], 0
	s_waitcnt lgkmcnt(0)
	v_mfma_f32_16x16x32_bf16 v[192:195], v[180:183], v[76:79], v[192:195]
	s_nop 0
	v_mfma_f32_16x16x32_bf16 v[188:191], v[176:179], v[80:83], v[188:191]
	v_mfma_f32_16x16x32_bf16 v[192:195], v[184:187], v[80:83], v[192:195]

.LBB0_390:
	s_nop 7
	v_exp_f32_e32 v2, v192
	v_exp_f32_e32 v240, v193
	v_exp_f32_e32 v241, v190
	v_exp_f32_e32 v242, v191
	v_exp_f32_e32 v0, v188
	v_exp_f32_e32 v3, v189
	v_exp_f32_e32 v191, v194
	v_exp_f32_e32 v192, v195
	v_cvt_pk_bf16_f32 v189, v241, v242
	v_cvt_pk_bf16_f32 v190, v2, v240
	v_cvt_pk_bf16_f32 v188, v0, v3
	v_cvt_pk_bf16_f32 v191, v191, v192
	s_waitcnt lgkmcnt(3)
	s_nop 0
	v_mfma_f32_16x16x32_bf16 v[60:63], v[160:163], v[188:191], v[60:63]
	s_waitcnt lgkmcnt(2)
	v_mfma_f32_16x16x32_bf16 v[56:59], v[156:159], v[188:191], v[56:59]
	s_waitcnt lgkmcnt(1)
	v_mfma_f32_16x16x32_bf16 v[52:55], v[164:167], v[188:191], v[52:55]
	s_waitcnt lgkmcnt(0)
	v_mfma_f32_16x16x32_bf16 v[48:51], v[168:171], v[188:191], v[48:51]
	v_mfma_f32_16x16x32_bf16 v[72:75], v[4:7], v[188:191], v[72:75]
.LBB0_391:
	s_sub_i32 s17, s24, s30
	s_cmp_lt_u32 s17, 9
	s_cselect_b64 s[70:71], -1, 0
	s_cmp_gt_u32 s17, 8
	s_cbranch_scc1 .LBB0_397
	s_cmp_lt_u32 s17, 6
	s_mov_b64 s[72:73], -1
	s_cbranch_scc1 .LBB0_394
	v_lshl_add_u32 v0, s17, 6, v233
	v_max_i32_e32 v188, 0xffffffef, v0
	v_max_i32_e32 v2, 0, v0
	v_lshl_add_u32 v193, v188, 2, s13
	v_max_i32_e32 v188, 0xffffffee, v0
	v_lshl_add_u32 v2, v2, 2, s13
	v_max_i32_e32 v3, -1, v0
	v_max_i32_e32 v240, -2, v0
	v_max_i32_e32 v241, -3, v0
	v_max_i32_e32 v242, -16, v0
	v_lshl_add_u32 v194, v188, 2, s13
	v_max_i32_e32 v0, 0xffffffed, v0
	v_lshl_add_u32 v3, v3, 2, s13
	v_lshl_add_u32 v240, v240, 2, s13
	v_lshl_add_u32 v241, v241, 2, s13
	v_lshl_add_u32 v242, v242, 2, s13
	v_lshl_add_u32 v0, v0, 2, s13
	ds_read_b32 v188, v2
	ds_read_b32 v189, v3 offset:4
	ds_read_b32 v190, v240 offset:8
	ds_read_b32 v191, v241 offset:12
	ds_read_b32 v192, v242 offset:64
	ds_read_b32 v193, v193 offset:68
	ds_read_b32 v194, v194 offset:72
	ds_read_b32 v195, v0 offset:76
	s_waitcnt lgkmcnt(4)
	v_mfma_f32_16x16x32_bf16 v[188:191], v[172:175], v[84:87], v[188:191]
	s_mov_b64 s[72:73], 0
	s_waitcnt lgkmcnt(0)
	v_mfma_f32_16x16x32_bf16 v[192:195], v[180:183], v[84:87], v[192:195]
	s_nop 0
	v_mfma_f32_16x16x32_bf16 v[188:191], v[176:179], v[88:91], v[188:191]
	v_mfma_f32_16x16x32_bf16 v[192:195], v[184:187], v[88:91], v[192:195]

.LBB0_396:
	s_nop 7
	v_exp_f32_e32 v2, v192
	v_exp_f32_e32 v240, v193
	v_exp_f32_e32 v241, v190
	v_exp_f32_e32 v242, v191
	v_exp_f32_e32 v0, v188
	v_exp_f32_e32 v3, v189
	v_exp_f32_e32 v191, v194
	v_exp_f32_e32 v192, v195
	v_cvt_pk_bf16_f32 v189, v241, v242
	v_cvt_pk_bf16_f32 v190, v2, v240
	v_cvt_pk_bf16_f32 v188, v0, v3
	v_cvt_pk_bf16_f32 v191, v191, v192
	s_waitcnt lgkmcnt(3)
	s_nop 0
	v_mfma_f32_16x16x32_bf16 v[40:43], v[160:163], v[188:191], v[40:43]
	s_waitcnt lgkmcnt(2)
	v_mfma_f32_16x16x32_bf16 v[36:39], v[156:159], v[188:191], v[36:39]
	s_waitcnt lgkmcnt(1)
	v_mfma_f32_16x16x32_bf16 v[32:35], v[164:167], v[188:191], v[32:35]
	s_waitcnt lgkmcnt(0)
	v_mfma_f32_16x16x32_bf16 v[28:31], v[168:171], v[188:191], v[28:31]
	v_mfma_f32_16x16x32_bf16 v[44:47], v[4:7], v[188:191], v[44:47]
.LBB0_397:
	s_sub_i32 s24, s24, s34
	s_cmp_lt_u32 s24, 9
	s_cselect_b64 s[72:73], -1, 0
	s_cmp_gt_u32 s24, 8
	s_cbranch_scc1 .LBB0_403
	s_cmp_lt_u32 s24, 6
	s_mov_b64 s[74:75], -1
	s_cbranch_scc1 .LBB0_400
	v_lshl_add_u32 v0, s24, 6, v233
	v_max_i32_e32 v188, 0xffffffef, v0
	v_max_i32_e32 v2, 0, v0
	v_lshl_add_u32 v193, v188, 2, s13
	v_max_i32_e32 v188, 0xffffffee, v0
	v_lshl_add_u32 v2, v2, 2, s13
	v_max_i32_e32 v3, -1, v0
	v_max_i32_e32 v240, -2, v0
	v_max_i32_e32 v241, -3, v0
	v_max_i32_e32 v242, -16, v0
	v_lshl_add_u32 v194, v188, 2, s13
	v_max_i32_e32 v0, 0xffffffed, v0
	v_lshl_add_u32 v3, v3, 2, s13
	v_lshl_add_u32 v240, v240, 2, s13
	v_lshl_add_u32 v241, v241, 2, s13
	v_lshl_add_u32 v242, v242, 2, s13
	v_lshl_add_u32 v0, v0, 2, s13
	ds_read_b32 v188, v2
	ds_read_b32 v189, v3 offset:4
	ds_read_b32 v190, v240 offset:8
	ds_read_b32 v191, v241 offset:12
	ds_read_b32 v192, v242 offset:64
	ds_read_b32 v193, v193 offset:68
	ds_read_b32 v194, v194 offset:72
	ds_read_b32 v195, v0 offset:76
	s_waitcnt lgkmcnt(4)
	v_mfma_f32_16x16x32_bf16 v[188:191], v[172:175], v[92:95], v[188:191]
	s_mov_b64 s[74:75], 0
	s_waitcnt lgkmcnt(0)
	v_mfma_f32_16x16x32_bf16 v[192:195], v[180:183], v[92:95], v[192:195]
	s_nop 0
	v_mfma_f32_16x16x32_bf16 v[188:191], v[176:179], v[96:99], v[188:191]
	v_mfma_f32_16x16x32_bf16 v[192:195], v[184:187], v[96:99], v[192:195]

.LBB0_407:
	s_cmp_lt_u32 s14, 6
	s_mov_b64 s[66:67], -1
	s_cbranch_scc1 .LBB0_409
	v_lshl_add_u32 v0, s14, 6, v234
	v_max_i32_e32 v188, 0xffffffef, v0
	v_max_i32_e32 v2, 0, v0
	v_lshl_add_u32 v193, v188, 2, s13
	v_max_i32_e32 v188, 0xffffffee, v0
	v_lshl_add_u32 v2, v2, 2, s13
	v_max_i32_e32 v3, -1, v0
	v_max_i32_e32 v240, -2, v0
	v_max_i32_e32 v241, -3, v0
	v_max_i32_e32 v242, -16, v0
	v_lshl_add_u32 v194, v188, 2, s13
	v_max_i32_e32 v0, 0xffffffed, v0
	v_lshl_add_u32 v3, v3, 2, s13
	v_lshl_add_u32 v240, v240, 2, s13
	v_lshl_add_u32 v241, v241, 2, s13
	v_lshl_add_u32 v242, v242, 2, s13
	v_lshl_add_u32 v0, v0, 2, s13
	ds_read_b32 v188, v2
	ds_read_b32 v189, v3 offset:4
	ds_read_b32 v190, v240 offset:8
	ds_read_b32 v191, v241 offset:12
	ds_read_b32 v192, v242 offset:64
	ds_read_b32 v193, v193 offset:68
	ds_read_b32 v194, v194 offset:72
	ds_read_b32 v195, v0 offset:76
	s_waitcnt lgkmcnt(4)
	v_mfma_f32_16x16x32_bf16 v[188:191], v[172:175], v[64:67], v[188:191]
	s_mov_b64 s[66:67], 0
	s_waitcnt lgkmcnt(0)
	v_mfma_f32_16x16x32_bf16 v[192:195], v[180:183], v[64:67], v[192:195]
	s_nop 0
	v_mfma_f32_16x16x32_bf16 v[188:191], v[176:179], v[68:71], v[188:191]
	v_mfma_f32_16x16x32_bf16 v[192:195], v[184:187], v[68:71], v[192:195]

.LBB0_412:
	s_cmp_lt_u32 s15, 6
	s_mov_b64 s[66:67], -1
	s_cbranch_scc1 .LBB0_414
	v_lshl_add_u32 v0, s15, 6, v234
	v_max_i32_e32 v188, 0xffffffef, v0
	v_max_i32_e32 v2, 0, v0
	v_lshl_add_u32 v193, v188, 2, s13
	v_max_i32_e32 v188, 0xffffffee, v0
	v_lshl_add_u32 v2, v2, 2, s13
	v_max_i32_e32 v3, -1, v0
	v_max_i32_e32 v240, -2, v0
	v_max_i32_e32 v241, -3, v0
	v_max_i32_e32 v242, -16, v0
	v_lshl_add_u32 v194, v188, 2, s13
	v_max_i32_e32 v0, 0xffffffed, v0
	v_lshl_add_u32 v3, v3, 2, s13
	v_lshl_add_u32 v240, v240, 2, s13
	v_lshl_add_u32 v241, v241, 2, s13
	v_lshl_add_u32 v242, v242, 2, s13
	v_lshl_add_u32 v0, v0, 2, s13
	ds_read_b32 v188, v2
	ds_read_b32 v189, v3 offset:4
	ds_read_b32 v190, v240 offset:8
	ds_read_b32 v191, v241 offset:12
	ds_read_b32 v192, v242 offset:64
	ds_read_b32 v193, v193 offset:68
	ds_read_b32 v194, v194 offset:72
	ds_read_b32 v195, v0 offset:76
	s_waitcnt lgkmcnt(4)
	v_mfma_f32_16x16x32_bf16 v[188:191], v[172:175], v[76:79], v[188:191]
	s_mov_b64 s[66:67], 0
	s_waitcnt lgkmcnt(0)
	v_mfma_f32_16x16x32_bf16 v[192:195], v[180:183], v[76:79], v[192:195]
	s_nop 0
	v_mfma_f32_16x16x32_bf16 v[188:191], v[176:179], v[80:83], v[188:191]
	v_mfma_f32_16x16x32_bf16 v[192:195], v[184:187], v[80:83], v[192:195]

.LBB0_417:
	s_cmp_lt_u32 s17, 6
	s_mov_b64 s[66:67], -1
	s_cbranch_scc1 .LBB0_419
	v_lshl_add_u32 v0, s17, 6, v234
	v_max_i32_e32 v188, 0xffffffef, v0
	v_max_i32_e32 v2, 0, v0
	v_lshl_add_u32 v193, v188, 2, s13
	v_max_i32_e32 v188, 0xffffffee, v0
	v_lshl_add_u32 v2, v2, 2, s13
	v_max_i32_e32 v3, -1, v0
	v_max_i32_e32 v240, -2, v0
	v_max_i32_e32 v241, -3, v0
	v_max_i32_e32 v242, -16, v0
	v_lshl_add_u32 v194, v188, 2, s13
	v_max_i32_e32 v0, 0xffffffed, v0
	v_lshl_add_u32 v3, v3, 2, s13
	v_lshl_add_u32 v240, v240, 2, s13
	v_lshl_add_u32 v241, v241, 2, s13
	v_lshl_add_u32 v242, v242, 2, s13
	v_lshl_add_u32 v0, v0, 2, s13
	ds_read_b32 v188, v2
	ds_read_b32 v189, v3 offset:4
	ds_read_b32 v190, v240 offset:8
	ds_read_b32 v191, v241 offset:12
	ds_read_b32 v192, v242 offset:64
	ds_read_b32 v193, v193 offset:68
	ds_read_b32 v194, v194 offset:72
	ds_read_b32 v195, v0 offset:76
	s_waitcnt lgkmcnt(4)
	v_mfma_f32_16x16x32_bf16 v[188:191], v[172:175], v[84:87], v[188:191]
	s_mov_b64 s[66:67], 0
	s_waitcnt lgkmcnt(0)
	v_mfma_f32_16x16x32_bf16 v[192:195], v[180:183], v[84:87], v[192:195]
	s_nop 0
	v_mfma_f32_16x16x32_bf16 v[188:191], v[176:179], v[88:91], v[188:191]
	v_mfma_f32_16x16x32_bf16 v[192:195], v[184:187], v[88:91], v[192:195]

.LBB0_422:
	s_cmp_lt_u32 s24, 6
	s_mov_b64 s[66:67], -1
	s_cbranch_scc1 .LBB0_424
	v_lshl_add_u32 v0, s24, 6, v234
	v_max_i32_e32 v188, 0xffffffef, v0
	v_max_i32_e32 v2, 0, v0
	v_lshl_add_u32 v193, v188, 2, s13
	v_max_i32_e32 v188, 0xffffffee, v0
	v_lshl_add_u32 v2, v2, 2, s13
	v_max_i32_e32 v3, -1, v0
	v_max_i32_e32 v240, -2, v0
	v_max_i32_e32 v241, -3, v0
	v_max_i32_e32 v242, -16, v0
	v_lshl_add_u32 v194, v188, 2, s13
	v_max_i32_e32 v0, 0xffffffed, v0
	v_lshl_add_u32 v3, v3, 2, s13
	v_lshl_add_u32 v240, v240, 2, s13
	v_lshl_add_u32 v241, v241, 2, s13
	v_lshl_add_u32 v242, v242, 2, s13
	v_lshl_add_u32 v0, v0, 2, s13
	ds_read_b32 v188, v2
	ds_read_b32 v189, v3 offset:4
	ds_read_b32 v190, v240 offset:8
	ds_read_b32 v191, v241 offset:12
	ds_read_b32 v192, v242 offset:64
	ds_read_b32 v193, v193 offset:68
	ds_read_b32 v194, v194 offset:72
	ds_read_b32 v195, v0 offset:76
	s_waitcnt lgkmcnt(4)
	v_mfma_f32_16x16x32_bf16 v[188:191], v[172:175], v[92:95], v[188:191]
	s_mov_b64 s[66:67], 0
	s_waitcnt lgkmcnt(0)
	v_mfma_f32_16x16x32_bf16 v[192:195], v[180:183], v[92:95], v[192:195]
	s_nop 0
	v_mfma_f32_16x16x32_bf16 v[188:191], v[176:179], v[96:99], v[188:191]
	v_mfma_f32_16x16x32_bf16 v[192:195], v[184:187], v[96:99], v[192:195]

.LBB0_426:
	s_nop 7
	v_exp_f32_e32 v2, v192
	v_exp_f32_e32 v240, v193
	v_exp_f32_e32 v241, v190
	v_exp_f32_e32 v242, v191
	v_exp_f32_e32 v0, v188
	v_exp_f32_e32 v3, v189
	v_exp_f32_e32 v155, v194
	s_waitcnt lgkmcnt(11)
	v_exp_f32_e32 v172, v195
	v_cvt_pk_bf16_f32 v153, v241, v242
	v_cvt_pk_bf16_f32 v154, v2, v240
	v_cvt_pk_bf16_f32 v152, v0, v3
	v_cvt_pk_bf16_f32 v155, v155, v172
	s_waitcnt lgkmcnt(3)
	s_nop 0
	v_mfma_f32_16x16x32_bf16 v[20:23], v[160:163], v[152:155], v[20:23]
	s_waitcnt lgkmcnt(2)
	v_mfma_f32_16x16x32_bf16 v[16:19], v[156:159], v[152:155], v[16:19]
	s_waitcnt lgkmcnt(1)
	v_mfma_f32_16x16x32_bf16 v[12:15], v[164:167], v[152:155], v[12:15]
	s_waitcnt lgkmcnt(0)
	v_mfma_f32_16x16x32_bf16 v[8:11], v[168:171], v[152:155], v[8:11]
	v_mfma_f32_16x16x32_bf16 v[24:27], v[4:7], v[152:155], v[24:27]

; #define AT_WAIT4(src) asm volatile("s_waitcnt vmcnt(4)" : "+v"(src[0]), "+v"(src[1]), "+v"(src[2]), "+v"(src[3]) :: "memory")
; #define AT_WAIT0(src) asm volatile("s_waitcnt vmcnt(0)" : "+v"(src[0]), "+v"(src[1]), "+v"(src[2]), "+v"(src[3]) :: "memory")
; #define AT_STORE(src, stage) do { _Pragma("unroll") for (int q_ = 0; q_ < 4; ++q_) *(LAS u32x4*)(wr0 + (stage) * AT_STAGE + q_ * AT_TILE) = src[q_]; } while (0)
; __device__ __forceinline__ void attn_unit(LAS unsigned char* lds, const bf16* PROJ, bf16* YMIX, float* ssq, const float* relb, const float* gqn, const float* gkn,
;                                           int b, int h, int c0, int wave, int lane_in, int tid_in) {
;     ...
;         if (jp + 2 < 8) AT_WAIT4(pb); else AT_WAIT0(pb);
;         AT_STORE(pb, 1);
;         if (jp + 3 < 8) AT_GLOAD(pb);
.LBB0_431:
	s_cmp_gt_u32 s18, 4
	s_cselect_b64 s[68:69], -1, 0
	s_and_b64 vcc, exec, s[68:69]
	ds_write_b128 v232, v[152:155] offset:36864
	s_waitcnt lgkmcnt(3)
	ds_write_b128 v232, v[156:159] offset:46080
	ds_write_b128 v232, v[160:163] offset:55296
	s_waitcnt lgkmcnt(4)
	ds_write_b128 v232, v[164:167] offset:64512
	s_cbranch_vccnz .LBB0_433
	global_load_dwordx4 v[112:115], v[210:211], off
	global_load_dwordx4 v[116:119], v[210:211], off offset:1024
	global_load_dwordx4 v[124:127], v[208:209], off
	global_load_dwordx4 v[128:131], v[208:209], off offset:1024
	v_lshl_add_u64 v[2:3], v[208:209], 0, s[52:53]
	v_lshl_add_u64 v[244:245], v[210:211], 0, s[52:53]
	v_mov_b64_e32 v[208:209], v[2:3]
	v_mov_b64_e32 v[210:211], v[244:245]
	s_branch .LBB0_434

; #define AT_WAIT4(src) asm volatile("s_waitcnt vmcnt(4)" : "+v"(src[0]), "+v"(src[1]), "+v"(src[2]), "+v"(src[3]) :: "memory")
; #define AT_WAIT0(src) asm volatile("s_waitcnt vmcnt(0)" : "+v"(src[0]), "+v"(src[1]), "+v"(src[2]), "+v"(src[3]) :: "memory")
; #define AT_STORE(src, stage) do { _Pragma("unroll") for (int q_ = 0; q_ < 4; ++q_) *(LAS u32x4*)(wr0 + (stage) * AT_STAGE + q_ * AT_TILE) = src[q_]; } while (0)
; __device__ __forceinline__ void attn_unit(LAS unsigned char* lds, const bf16* PROJ, bf16* YMIX, float* ssq, const float* relb, const float* gqn, const float* gkn,
;                                           int b, int h, int c0, int wave, int lane_in, int tid_in) {
;     ...
;     typedef short v4i16_t __attribute__((ext_vector_type(4)));
;     for (int jp = j0 >> 1; jp < 8; jp += 2) {
;         __syncthreads();
;         AT_STEP(2 * jp, 0);
;         AT_STEP(2 * jp + 1, 2 * AT_TILE);
;         if (jp + 2 < 8) AT_WAIT4(pb); else AT_WAIT0(pb);
;         AT_STORE(pb, 1);
;         if (jp + 3 < 8) AT_GLOAD(pb);
;         __syncthreads();
;         AT_STEP(2 * jp + 2, AT_STAGE);
.LBB0_434:
	v_mov_b32_e32 v0, s13
	s_waitcnt lgkmcnt(0)
	s_barrier
	ds_read_b32 v152, v0
	ds_read_b128 v[172:175], v237 offset:36864
	ds_read_b128 v[176:179], v237 offset:36928
	ds_read_b128 v[180:183], v237 offset:39168
	ds_read_b128 v[184:187], v237 offset:39232
	ds_read_b64_tr_b16 v[160:161], v238 offset:46080
	ds_read_b64_tr_b16 v[156:157], v238 offset:46112
	ds_read_b64_tr_b16 v[164:165], v238 offset:46144
	ds_read_b64_tr_b16 v[168:169], v238 offset:46176
	ds_read_b64_tr_b16 v[162:163], v239 offset:46080
	ds_read_b64_tr_b16 v[158:159], v239 offset:46112
	ds_read_b64_tr_b16 v[166:167], v239 offset:46144
	ds_read_b64_tr_b16 v[170:171], v239 offset:46176
	s_or_b32 s17, s20, 2
	s_sub_i32 s14, s17, s85
	s_cmp_lt_u32 s14, 9
	s_waitcnt lgkmcnt(12)
	v_mov_b32_e32 v153, v152
	v_mov_b32_e32 v154, v152
	s_cselect_b64 s[70:71], -1, 0
	s_cmp_gt_u32 s14, 8
	v_mov_b32_e32 v155, v152
	s_cbranch_scc1 .LBB0_440
	s_cmp_lt_u32 s14, 6
	s_mov_b64 s[72:73], -1
	s_cbranch_scc1 .LBB0_437
	v_lshl_add_u32 v0, s14, 6, v233
	v_max_i32_e32 v188, 0xffffffef, v0
	v_max_i32_e32 v2, 0, v0
	v_lshl_add_u32 v193, v188, 2, s13
	v_max_i32_e32 v188, 0xffffffee, v0
	v_lshl_add_u32 v2, v2, 2, s13
	v_max_i32_e32 v3, -1, v0
	v_max_i32_e32 v240, -2, v0
	v_max_i32_e32 v241, -3, v0
	v_max_i32_e32 v242, -16, v0
	v_lshl_add_u32 v194, v188, 2, s13
	v_max_i32_e32 v0, 0xffffffed, v0
	v_lshl_add_u32 v3, v3, 2, s13
	v_lshl_add_u32 v240, v240, 2, s13
	v_lshl_add_u32 v241, v241, 2, s13
	v_lshl_add_u32 v242, v242, 2, s13
	v_lshl_add_u32 v0, v0, 2, s13
	ds_read_b32 v188, v2
	ds_read_b32 v189, v3 offset:4
	ds_read_b32 v190, v240 offset:8
	ds_read_b32 v191, v241 offset:12
	ds_read_b32 v192, v242 offset:64
	ds_read_b32 v193, v193 offset:68
	ds_read_b32 v194, v194 offset:72
	ds_read_b32 v195, v0 offset:76
	s_waitcnt lgkmcnt(4)
	v_mfma_f32_16x16x32_bf16 v[188:191], v[172:175], v[64:67], v[188:191]
	s_mov_b64 s[72:73], 0
	s_waitcnt lgkmcnt(0)
	v_mfma_f32_16x16x32_bf16 v[192:195], v[180:183], v[64:67], v[192:195]
	s_nop 0
	v_mfma_f32_16x16x32_bf16 v[188:191], v[176:179], v[68:71], v[188:191]
	v_mfma_f32_16x16x32_bf16 v[192:195], v[184:187], v[68:71], v[192:195]

.LBB0_440:
	s_and_b64 vcc, exec, s[4:5]
	s_cbranch_vccnz .LBB0_446
	s_cmp_lt_u32 s21, 6
	s_mov_b64 s[72:73], -1
	s_cbranch_scc1 .LBB0_443
	v_lshl_add_u32 v0, s21, 6, v233
	v_max_i32_e32 v188, 0xffffffef, v0
	v_max_i32_e32 v2, 0, v0
	v_lshl_add_u32 v193, v188, 2, s13
	v_max_i32_e32 v188, 0xffffffee, v0
	v_lshl_add_u32 v2, v2, 2, s13
	v_max_i32_e32 v3, -1, v0
	v_max_i32_e32 v240, -2, v0
	v_max_i32_e32 v241, -3, v0
	v_max_i32_e32 v242, -16, v0
	v_lshl_add_u32 v194, v188, 2, s13
	v_max_i32_e32 v0, 0xffffffed, v0
	v_lshl_add_u32 v3, v3, 2, s13
	v_lshl_add_u32 v240, v240, 2, s13
	v_lshl_add_u32 v241, v241, 2, s13
	v_lshl_add_u32 v242, v242, 2, s13
	v_lshl_add_u32 v0, v0, 2, s13
	ds_read_b32 v188, v2
	ds_read_b32 v189, v3 offset:4
	ds_read_b32 v190, v240 offset:8
	ds_read_b32 v191, v241 offset:12
	ds_read_b32 v192, v242 offset:64
	ds_read_b32 v193, v193 offset:68
	ds_read_b32 v194, v194 offset:72
	ds_read_b32 v195, v0 offset:76
	s_waitcnt lgkmcnt(4)
	v_mfma_f32_16x16x32_bf16 v[188:191], v[172:175], v[76:79], v[188:191]
	s_mov_b64 s[72:73], 0
	s_waitcnt lgkmcnt(0)
	v_mfma_f32_16x16x32_bf16 v[192:195], v[180:183], v[76:79], v[192:195]
	s_nop 0
	v_mfma_f32_16x16x32_bf16 v[188:191], v[176:179], v[80:83], v[188:191]
	v_mfma_f32_16x16x32_bf16 v[192:195], v[184:187], v[80:83], v[192:195]

.LBB0_446:
	s_sub_i32 s15, s17, s30
	s_cmp_lt_u32 s15, 9
	s_cselect_b64 s[72:73], -1, 0
	s_cmp_gt_u32 s15, 8
	s_cbranch_scc1 .LBB0_452
	s_cmp_lt_u32 s15, 6
	s_mov_b64 s[74:75], -1
	s_cbranch_scc1 .LBB0_449
	v_lshl_add_u32 v0, s15, 6, v233
	v_max_i32_e32 v188, 0xffffffef, v0
	v_max_i32_e32 v2, 0, v0
	v_lshl_add_u32 v193, v188, 2, s13
	v_max_i32_e32 v188, 0xffffffee, v0
	v_lshl_add_u32 v2, v2, 2, s13
	v_max_i32_e32 v3, -1, v0
	v_max_i32_e32 v240, -2, v0
	v_max_i32_e32 v241, -3, v0
	v_max_i32_e32 v242, -16, v0
	v_lshl_add_u32 v194, v188, 2, s13
	v_max_i32_e32 v0, 0xffffffed, v0
	v_lshl_add_u32 v3, v3, 2, s13
	v_lshl_add_u32 v240, v240, 2, s13
	v_lshl_add_u32 v241, v241, 2, s13
	v_lshl_add_u32 v242, v242, 2, s13
	v_lshl_add_u32 v0, v0, 2, s13
	ds_read_b32 v188, v2
	ds_read_b32 v189, v3 offset:4
	ds_read_b32 v190, v240 offset:8
	ds_read_b32 v191, v241 offset:12
	ds_read_b32 v192, v242 offset:64
	ds_read_b32 v193, v193 offset:68
	ds_read_b32 v194, v194 offset:72
	ds_read_b32 v195, v0 offset:76
	s_waitcnt lgkmcnt(4)
	v_mfma_f32_16x16x32_bf16 v[188:191], v[172:175], v[84:87], v[188:191]
	s_mov_b64 s[74:75], 0
	s_waitcnt lgkmcnt(0)
	v_mfma_f32_16x16x32_bf16 v[192:195], v[180:183], v[84:87], v[192:195]
	s_nop 0
	v_mfma_f32_16x16x32_bf16 v[188:191], v[176:179], v[88:91], v[188:191]
	v_mfma_f32_16x16x32_bf16 v[192:195], v[184:187], v[88:91], v[192:195]

.LBB0_452:
	s_sub_i32 s17, s17, s34
	s_cmp_lt_u32 s17, 9
	s_cselect_b64 s[74:75], -1, 0
	s_cmp_gt_u32 s17, 8
	s_cbranch_scc1 .LBB0_458
	s_cmp_lt_u32 s17, 6
	s_mov_b64 s[76:77], -1
	s_cbranch_scc1 .LBB0_455
	v_lshl_add_u32 v0, s17, 6, v233
	v_max_i32_e32 v188, 0xffffffef, v0
	v_max_i32_e32 v2, 0, v0
	v_lshl_add_u32 v193, v188, 2, s13
	v_max_i32_e32 v188, 0xffffffee, v0
	v_lshl_add_u32 v2, v2, 2, s13
	v_max_i32_e32 v3, -1, v0
	v_max_i32_e32 v240, -2, v0
	v_max_i32_e32 v241, -3, v0
	v_max_i32_e32 v242, -16, v0
	v_lshl_add_u32 v194, v188, 2, s13
	v_max_i32_e32 v0, 0xffffffed, v0
	v_lshl_add_u32 v3, v3, 2, s13
	v_lshl_add_u32 v240, v240, 2, s13
	v_lshl_add_u32 v241, v241, 2, s13
	v_lshl_add_u32 v242, v242, 2, s13
	v_lshl_add_u32 v0, v0, 2, s13
	ds_read_b32 v188, v2
	ds_read_b32 v189, v3 offset:4
	ds_read_b32 v190, v240 offset:8
	ds_read_b32 v191, v241 offset:12
	ds_read_b32 v192, v242 offset:64
	ds_read_b32 v193, v193 offset:68
	ds_read_b32 v194, v194 offset:72
	ds_read_b32 v195, v0 offset:76
	s_waitcnt lgkmcnt(4)
	v_mfma_f32_16x16x32_bf16 v[188:191], v[172:175], v[92:95], v[188:191]
	s_mov_b64 s[76:77], 0
	s_waitcnt lgkmcnt(0)
	v_mfma_f32_16x16x32_bf16 v[192:195], v[180:183], v[92:95], v[192:195]
	s_nop 0
	v_mfma_f32_16x16x32_bf16 v[188:191], v[176:179], v[96:99], v[188:191]
	v_mfma_f32_16x16x32_bf16 v[192:195], v[184:187], v[96:99], v[192:195]

.LBB0_462:
	s_cmp_lt_u32 s14, 6
	s_mov_b64 s[70:71], -1
	s_cbranch_scc1 .LBB0_464
	v_lshl_add_u32 v0, s14, 6, v234
	v_max_i32_e32 v188, 0xffffffef, v0
	v_max_i32_e32 v2, 0, v0
	v_lshl_add_u32 v193, v188, 2, s13
	v_max_i32_e32 v188, 0xffffffee, v0
	v_lshl_add_u32 v2, v2, 2, s13
	v_max_i32_e32 v3, -1, v0
	v_max_i32_e32 v240, -2, v0
	v_max_i32_e32 v241, -3, v0
	v_max_i32_e32 v242, -16, v0
	v_lshl_add_u32 v194, v188, 2, s13
	v_max_i32_e32 v0, 0xffffffed, v0
	v_lshl_add_u32 v3, v3, 2, s13
	v_lshl_add_u32 v240, v240, 2, s13
	v_lshl_add_u32 v241, v241, 2, s13
	v_lshl_add_u32 v242, v242, 2, s13
	v_lshl_add_u32 v0, v0, 2, s13
	ds_read_b32 v188, v2
	ds_read_b32 v189, v3 offset:4
	ds_read_b32 v190, v240 offset:8
	ds_read_b32 v191, v241 offset:12
	ds_read_b32 v192, v242 offset:64
	ds_read_b32 v193, v193 offset:68
	ds_read_b32 v194, v194 offset:72
	ds_read_b32 v195, v0 offset:76
	s_waitcnt lgkmcnt(4)
	v_mfma_f32_16x16x32_bf16 v[188:191], v[172:175], v[64:67], v[188:191]
	s_mov_b64 s[70:71], 0
	s_waitcnt lgkmcnt(0)
	v_mfma_f32_16x16x32_bf16 v[192:195], v[180:183], v[64:67], v[192:195]
	s_nop 0
	v_mfma_f32_16x16x32_bf16 v[188:191], v[176:179], v[68:71], v[188:191]
	v_mfma_f32_16x16x32_bf16 v[192:195], v[184:187], v[68:71], v[192:195]

.LBB0_466:
	s_nop 7
	v_exp_f32_e32 v2, v192
	v_exp_f32_e32 v240, v193
	v_exp_f32_e32 v241, v190
	v_exp_f32_e32 v242, v191
	v_exp_f32_e32 v0, v188
	v_exp_f32_e32 v3, v189
	v_exp_f32_e32 v191, v194
	v_exp_f32_e32 v192, v195
	v_cvt_pk_bf16_f32 v189, v241, v242
	v_cvt_pk_bf16_f32 v190, v2, v240
	v_cvt_pk_bf16_f32 v188, v0, v3
	v_cvt_pk_bf16_f32 v191, v191, v192
	s_waitcnt lgkmcnt(3)
	s_nop 0
	v_mfma_f32_16x16x32_bf16 v[120:123], v[160:163], v[188:191], v[120:123]
	s_waitcnt lgkmcnt(2)
	v_mfma_f32_16x16x32_bf16 v[108:111], v[156:159], v[188:191], v[108:111]
	s_waitcnt lgkmcnt(1)
	v_mfma_f32_16x16x32_bf16 v[104:107], v[164:167], v[188:191], v[104:107]
	s_waitcnt lgkmcnt(0)
	v_mfma_f32_16x16x32_bf16 v[100:103], v[168:171], v[188:191], v[100:103]
	v_mfma_f32_16x16x32_bf16 v[136:139], v[4:7], v[188:191], v[136:139]
	s_and_b64 vcc, exec, s[4:5]
	s_cbranch_vccnz .LBB0_460
.LBB0_467:
	s_cmp_lt_u32 s21, 6
	s_mov_b64 s[4:5], -1
	s_cbranch_scc1 .LBB0_469
	v_lshl_add_u32 v0, s21, 6, v234
	v_max_i32_e32 v188, 0xffffffef, v0
	v_max_i32_e32 v2, 0, v0
	v_lshl_add_u32 v193, v188, 2, s13
	v_max_i32_e32 v188, 0xffffffee, v0
	v_lshl_add_u32 v2, v2, 2, s13
	v_max_i32_e32 v3, -1, v0
	v_max_i32_e32 v240, -2, v0
	v_max_i32_e32 v241, -3, v0
	v_max_i32_e32 v242, -16, v0
	v_lshl_add_u32 v194, v188, 2, s13
	v_max_i32_e32 v0, 0xffffffed, v0
	v_lshl_add_u32 v3, v3, 2, s13
	v_lshl_add_u32 v240, v240, 2, s13
	v_lshl_add_u32 v241, v241, 2, s13
	v_lshl_add_u32 v242, v242, 2, s13
	v_lshl_add_u32 v0, v0, 2, s13
	ds_read_b32 v188, v2
	ds_read_b32 v189, v3 offset:4
	ds_read_b32 v190, v240 offset:8
	ds_read_b32 v191, v241 offset:12
	ds_read_b32 v192, v242 offset:64
	ds_read_b32 v193, v193 offset:68
	ds_read_b32 v194, v194 offset:72
	ds_read_b32 v195, v0 offset:76
	s_waitcnt lgkmcnt(4)
	v_mfma_f32_16x16x32_bf16 v[188:191], v[172:175], v[76:79], v[188:191]
	s_mov_b64 s[4:5], 0
	s_waitcnt lgkmcnt(0)
	v_mfma_f32_16x16x32_bf16 v[192:195], v[180:183], v[76:79], v[192:195]
	s_nop 0
	v_mfma_f32_16x16x32_bf16 v[188:191], v[176:179], v[80:83], v[188:191]
	v_mfma_f32_16x16x32_bf16 v[192:195], v[184:187], v[80:83], v[192:195]

.LBB0_471:
	s_nop 7
	v_exp_f32_e32 v2, v192
	v_exp_f32_e32 v240, v193
	v_exp_f32_e32 v241, v190
	v_exp_f32_e32 v242, v191
	v_exp_f32_e32 v0, v188
	v_exp_f32_e32 v3, v189
	v_exp_f32_e32 v191, v194
	v_exp_f32_e32 v192, v195
	v_cvt_pk_bf16_f32 v189, v241, v242
	v_cvt_pk_bf16_f32 v190, v2, v240
	v_cvt_pk_bf16_f32 v188, v0, v3
	v_cvt_pk_bf16_f32 v191, v191, v192
	s_waitcnt lgkmcnt(3)
	s_nop 0
	v_mfma_f32_16x16x32_bf16 v[60:63], v[160:163], v[188:191], v[60:63]
	s_waitcnt lgkmcnt(2)
	v_mfma_f32_16x16x32_bf16 v[56:59], v[156:159], v[188:191], v[56:59]
	s_waitcnt lgkmcnt(1)
	v_mfma_f32_16x16x32_bf16 v[52:55], v[164:167], v[188:191], v[52:55]
	s_waitcnt lgkmcnt(0)
	v_mfma_f32_16x16x32_bf16 v[48:51], v[168:171], v[188:191], v[48:51]
	v_mfma_f32_16x16x32_bf16 v[72:75], v[4:7], v[188:191], v[72:75]
	s_andn2_b64 vcc, exec, s[72:73]
	s_cbranch_vccnz .LBB0_461
.LBB0_472:
	s_cmp_lt_u32 s15, 6
	s_mov_b64 s[4:5], -1
	s_cbranch_scc1 .LBB0_474
	v_lshl_add_u32 v0, s15, 6, v234
	v_max_i32_e32 v188, 0xffffffef, v0
	v_max_i32_e32 v2, 0, v0
	v_lshl_add_u32 v193, v188, 2, s13
	v_max_i32_e32 v188, 0xffffffee, v0
	v_lshl_add_u32 v2, v2, 2, s13
	v_max_i32_e32 v3, -1, v0
	v_max_i32_e32 v240, -2, v0
	v_max_i32_e32 v241, -3, v0
	v_max_i32_e32 v242, -16, v0
	v_lshl_add_u32 v194, v188, 2, s13
	v_max_i32_e32 v0, 0xffffffed, v0
	v_lshl_add_u32 v3, v3, 2, s13
	v_lshl_add_u32 v240, v240, 2, s13
	v_lshl_add_u32 v241, v241, 2, s13
	v_lshl_add_u32 v242, v242, 2, s13
	v_lshl_add_u32 v0, v0, 2, s13
	ds_read_b32 v188, v2
	ds_read_b32 v189, v3 offset:4
	ds_read_b32 v190, v240 offset:8
	ds_read_b32 v191, v241 offset:12
	ds_read_b32 v192, v242 offset:64
	ds_read_b32 v193, v193 offset:68
	ds_read_b32 v194, v194 offset:72
	ds_read_b32 v195, v0 offset:76
	s_waitcnt lgkmcnt(4)
	v_mfma_f32_16x16x32_bf16 v[188:191], v[172:175], v[84:87], v[188:191]
	s_mov_b64 s[4:5], 0
	s_waitcnt lgkmcnt(0)
	v_mfma_f32_16x16x32_bf16 v[192:195], v[180:183], v[84:87], v[192:195]
	s_nop 0
	v_mfma_f32_16x16x32_bf16 v[188:191], v[176:179], v[88:91], v[188:191]
	v_mfma_f32_16x16x32_bf16 v[192:195], v[184:187], v[88:91], v[192:195]

.LBB0_476:
	s_nop 7
	v_exp_f32_e32 v2, v192
	v_exp_f32_e32 v240, v193
	v_exp_f32_e32 v241, v190
	v_exp_f32_e32 v242, v191
	v_exp_f32_e32 v0, v188
	v_exp_f32_e32 v3, v189
	v_exp_f32_e32 v191, v194
	v_exp_f32_e32 v192, v195
	v_cvt_pk_bf16_f32 v189, v241, v242
	v_cvt_pk_bf16_f32 v190, v2, v240
	v_cvt_pk_bf16_f32 v188, v0, v3
	v_cvt_pk_bf16_f32 v191, v191, v192
	s_waitcnt lgkmcnt(3)
	s_nop 0
	v_mfma_f32_16x16x32_bf16 v[40:43], v[160:163], v[188:191], v[40:43]
	s_waitcnt lgkmcnt(2)
	v_mfma_f32_16x16x32_bf16 v[36:39], v[156:159], v[188:191], v[36:39]
	s_waitcnt lgkmcnt(1)
	v_mfma_f32_16x16x32_bf16 v[32:35], v[164:167], v[188:191], v[32:35]
	s_waitcnt lgkmcnt(0)
	v_mfma_f32_16x16x32_bf16 v[28:31], v[168:171], v[188:191], v[28:31]
	v_mfma_f32_16x16x32_bf16 v[44:47], v[4:7], v[188:191], v[44:47]
	s_andn2_b64 vcc, exec, s[74:75]
	s_cbranch_vccnz .LBB0_482
.LBB0_477:
	s_cmp_lt_u32 s17, 6
	s_mov_b64 s[4:5], -1
	s_cbranch_scc1 .LBB0_479
	v_lshl_add_u32 v0, s17, 6, v234
	v_max_i32_e32 v188, 0xffffffef, v0
	v_max_i32_e32 v2, 0, v0
	v_lshl_add_u32 v193, v188, 2, s13
	v_max_i32_e32 v188, 0xffffffee, v0
	v_lshl_add_u32 v2, v2, 2, s13
	v_max_i32_e32 v3, -1, v0
	v_max_i32_e32 v240, -2, v0
	v_max_i32_e32 v241, -3, v0
	v_max_i32_e32 v242, -16, v0
	v_lshl_add_u32 v194, v188, 2, s13
	v_max_i32_e32 v0, 0xffffffed, v0
	v_lshl_add_u32 v3, v3, 2, s13
	v_lshl_add_u32 v240, v240, 2, s13
	v_lshl_add_u32 v241, v241, 2, s13
	v_lshl_add_u32 v242, v242, 2, s13
	v_lshl_add_u32 v0, v0, 2, s13
	ds_read_b32 v188, v2
	ds_read_b32 v189, v3 offset:4
	ds_read_b32 v190, v240 offset:8
	ds_read_b32 v191, v241 offset:12
	ds_read_b32 v192, v242 offset:64
	ds_read_b32 v193, v193 offset:68
	ds_read_b32 v194, v194 offset:72
	ds_read_b32 v195, v0 offset:76
	s_waitcnt lgkmcnt(4)
	v_mfma_f32_16x16x32_bf16 v[188:191], v[172:175], v[92:95], v[188:191]
	s_mov_b64 s[4:5], 0
	s_waitcnt lgkmcnt(0)
	v_mfma_f32_16x16x32_bf16 v[192:195], v[180:183], v[92:95], v[192:195]
	s_nop 0
	v_mfma_f32_16x16x32_bf16 v[188:191], v[176:179], v[96:99], v[188:191]
	v_mfma_f32_16x16x32_bf16 v[192:195], v[184:187], v[96:99], v[192:195]

; #define AT_WAIT4(src) asm volatile("s_waitcnt vmcnt(4)" : "+v"(src[0]), "+v"(src[1]), "+v"(src[2]), "+v"(src[3]) :: "memory")
; #define AT_WAIT0(src) asm volatile("s_waitcnt vmcnt(0)" : "+v"(src[0]), "+v"(src[1]), "+v"(src[2]), "+v"(src[3]) :: "memory")
; #define AT_STORE(src, stage) do { _Pragma("unroll") for (int q_ = 0; q_ < 4; ++q_) *(LAS u32x4*)(wr0 + (stage) * AT_STAGE + q_ * AT_TILE) = src[q_]; } while (0)
; __device__ __forceinline__ void attn_unit(LAS unsigned char* lds, const bf16* PROJ, bf16* YMIX, float* ssq, const float* relb, const float* gqn, const float* gkn,
;                                           int b, int h, int c0, int wave, int lane_in, int tid_in) {
;     ...
;     typedef short v4i16_t __attribute__((ext_vector_type(4)));
;     for (int jp = j0 >> 1; jp < 8; jp += 2) {
;         __syncthreads();
;         AT_STEP(2 * jp, 0);
;         AT_STEP(2 * jp + 1, 2 * AT_TILE);
;         if (jp + 2 < 8) AT_WAIT4(pb); else AT_WAIT0(pb);
;         AT_STORE(pb, 1);
;         if (jp + 3 < 8) AT_GLOAD(pb);
;         __syncthreads();
;         AT_STEP(2 * jp + 2, AT_STAGE);
;         AT_STEP(2 * jp + 3, AT_STAGE + 2 * AT_TILE);
.LBB0_482:
	s_waitcnt lgkmcnt(11)
	ds_read_b128 v[172:175], v237 offset:55296
	s_waitcnt lgkmcnt(11)
	ds_read_b128 v[176:179], v237 offset:55360
	s_waitcnt lgkmcnt(11)
	ds_read_b128 v[180:183], v237 offset:57600
	s_waitcnt lgkmcnt(11)
	ds_read_b128 v[184:187], v237 offset:57664
	s_waitcnt lgkmcnt(11)
	ds_read_b64_tr_b16 v[160:161], v238 offset:64512
	s_waitcnt lgkmcnt(11)
	ds_read_b64_tr_b16 v[156:157], v238 offset:64544
	s_waitcnt lgkmcnt(11)
	ds_read_b64_tr_b16 v[164:165], v238 offset:64576
	s_waitcnt lgkmcnt(11)
	ds_read_b64_tr_b16 v[168:169], v238 offset:64608
	s_waitcnt lgkmcnt(11)
	ds_read_b64_tr_b16 v[162:163], v239 offset:64512
	s_waitcnt lgkmcnt(11)
	ds_read_b64_tr_b16 v[158:159], v239 offset:64544
	s_waitcnt lgkmcnt(11)
	ds_read_b64_tr_b16 v[166:167], v239 offset:64576
	s_waitcnt lgkmcnt(11)
	ds_read_b64_tr_b16 v[170:171], v239 offset:64608
	s_or_b32 s20, s20, 3
	s_sub_i32 s14, s20, s85
	s_cmp_lt_u32 s14, 9
	s_cselect_b64 s[4:5], -1, 0
	s_cmp_gt_u32 s14, 8
	s_cbranch_scc1 .LBB0_488
	s_cmp_lt_u32 s14, 6
	s_mov_b64 s[70:71], -1
	s_cbranch_scc1 .LBB0_485
	v_lshl_add_u32 v0, s14, 6, v233
	v_max_i32_e32 v188, 0xffffffef, v0
	v_max_i32_e32 v2, 0, v0
	v_lshl_add_u32 v193, v188, 2, s13
	v_max_i32_e32 v188, 0xffffffee, v0
	v_lshl_add_u32 v2, v2, 2, s13
	v_max_i32_e32 v3, -1, v0
	v_max_i32_e32 v240, -2, v0
	v_max_i32_e32 v241, -3, v0
	v_max_i32_e32 v242, -16, v0
	v_lshl_add_u32 v194, v188, 2, s13
	v_max_i32_e32 v0, 0xffffffed, v0
	v_lshl_add_u32 v3, v3, 2, s13
	v_lshl_add_u32 v240, v240, 2, s13
	v_lshl_add_u32 v241, v241, 2, s13
	v_lshl_add_u32 v242, v242, 2, s13
	v_lshl_add_u32 v0, v0, 2, s13
	ds_read_b32 v188, v2
	ds_read_b32 v189, v3 offset:4
	ds_read_b32 v190, v240 offset:8
	ds_read_b32 v191, v241 offset:12
	ds_read_b32 v192, v242 offset:64
	ds_read_b32 v193, v193 offset:68
	ds_read_b32 v194, v194 offset:72
	ds_read_b32 v195, v0 offset:76
	s_waitcnt lgkmcnt(4)
	v_mfma_f32_16x16x32_bf16 v[188:191], v[172:175], v[64:67], v[188:191]
	s_mov_b64 s[70:71], 0
	s_waitcnt lgkmcnt(0)
	v_mfma_f32_16x16x32_bf16 v[192:195], v[180:183], v[64:67], v[192:195]
	s_nop 0
	v_mfma_f32_16x16x32_bf16 v[188:191], v[176:179], v[68:71], v[188:191]
	v_mfma_f32_16x16x32_bf16 v[192:195], v[184:187], v[68:71], v[192:195]

.LBB0_488:
	s_sub_i32 s15, s20, s19
	s_cmp_lt_u32 s15, 9
	s_cselect_b64 s[70:71], -1, 0
	s_cmp_gt_u32 s15, 8
	s_cbranch_scc1 .LBB0_494
	s_cmp_lt_u32 s15, 6
	s_mov_b64 s[72:73], -1
	s_cbranch_scc1 .LBB0_491
	v_lshl_add_u32 v0, s15, 6, v233
	v_max_i32_e32 v188, 0xffffffef, v0
	v_max_i32_e32 v2, 0, v0
	v_lshl_add_u32 v193, v188, 2, s13
	v_max_i32_e32 v188, 0xffffffee, v0
	v_lshl_add_u32 v2, v2, 2, s13
	v_max_i32_e32 v3, -1, v0
	v_max_i32_e32 v240, -2, v0
	v_max_i32_e32 v241, -3, v0
	v_max_i32_e32 v242, -16, v0
	v_lshl_add_u32 v194, v188, 2, s13
	v_max_i32_e32 v0, 0xffffffed, v0
	v_lshl_add_u32 v3, v3, 2, s13
	v_lshl_add_u32 v240, v240, 2, s13
	v_lshl_add_u32 v241, v241, 2, s13
	v_lshl_add_u32 v242, v242, 2, s13
	v_lshl_add_u32 v0, v0, 2, s13
	ds_read_b32 v188, v2
	ds_read_b32 v189, v3 offset:4
	ds_read_b32 v190, v240 offset:8
	ds_read_b32 v191, v241 offset:12
	ds_read_b32 v192, v242 offset:64
	ds_read_b32 v193, v193 offset:68
	ds_read_b32 v194, v194 offset:72
	ds_read_b32 v195, v0 offset:76
	s_waitcnt lgkmcnt(4)
	v_mfma_f32_16x16x32_bf16 v[188:191], v[172:175], v[76:79], v[188:191]
	s_mov_b64 s[72:73], 0
	s_waitcnt lgkmcnt(0)
	v_mfma_f32_16x16x32_bf16 v[192:195], v[180:183], v[76:79], v[192:195]
	s_nop 0
	v_mfma_f32_16x16x32_bf16 v[188:191], v[176:179], v[80:83], v[188:191]
	v_mfma_f32_16x16x32_bf16 v[192:195], v[184:187], v[80:83], v[192:195]

.LBB0_494:
	s_sub_i32 s17, s20, s30
	s_cmp_lt_u32 s17, 9
	s_cselect_b64 s[72:73], -1, 0
	s_cmp_gt_u32 s17, 8
	s_cbranch_scc1 .LBB0_500
	s_cmp_lt_u32 s17, 6
	s_mov_b64 s[74:75], -1
	s_cbranch_scc1 .LBB0_497
	v_lshl_add_u32 v0, s17, 6, v233
	v_max_i32_e32 v188, 0xffffffef, v0
	v_max_i32_e32 v2, 0, v0
	v_lshl_add_u32 v193, v188, 2, s13
	v_max_i32_e32 v188, 0xffffffee, v0
	v_lshl_add_u32 v2, v2, 2, s13
	v_max_i32_e32 v3, -1, v0
	v_max_i32_e32 v240, -2, v0
	v_max_i32_e32 v241, -3, v0
	v_max_i32_e32 v242, -16, v0
	v_lshl_add_u32 v194, v188, 2, s13
	v_max_i32_e32 v0, 0xffffffed, v0
	v_lshl_add_u32 v3, v3, 2, s13
	v_lshl_add_u32 v240, v240, 2, s13
	v_lshl_add_u32 v241, v241, 2, s13
	v_lshl_add_u32 v242, v242, 2, s13
	v_lshl_add_u32 v0, v0, 2, s13
	ds_read_b32 v188, v2
	ds_read_b32 v189, v3 offset:4
	ds_read_b32 v190, v240 offset:8
	ds_read_b32 v191, v241 offset:12
	ds_read_b32 v192, v242 offset:64
	ds_read_b32 v193, v193 offset:68
	ds_read_b32 v194, v194 offset:72
	ds_read_b32 v195, v0 offset:76
	s_waitcnt lgkmcnt(4)
	v_mfma_f32_16x16x32_bf16 v[188:191], v[172:175], v[84:87], v[188:191]
	s_mov_b64 s[74:75], 0
	s_waitcnt lgkmcnt(0)
	v_mfma_f32_16x16x32_bf16 v[192:195], v[180:183], v[84:87], v[192:195]
	s_nop 0
	v_mfma_f32_16x16x32_bf16 v[188:191], v[176:179], v[88:91], v[188:191]
	v_mfma_f32_16x16x32_bf16 v[192:195], v[184:187], v[88:91], v[192:195]

.LBB0_500:
	s_sub_i32 s20, s20, s34
	s_cmp_lt_u32 s20, 9
	s_cselect_b64 s[74:75], -1, 0
	s_cmp_gt_u32 s20, 8
	s_cbranch_scc1 .LBB0_506
	s_cmp_lt_u32 s20, 6
	s_mov_b64 s[76:77], -1
	s_cbranch_scc1 .LBB0_503
	v_lshl_add_u32 v0, s20, 6, v233
	v_max_i32_e32 v188, 0xffffffef, v0
	v_max_i32_e32 v2, 0, v0
	v_lshl_add_u32 v193, v188, 2, s13
	v_max_i32_e32 v188, 0xffffffee, v0
	v_lshl_add_u32 v2, v2, 2, s13
	v_max_i32_e32 v3, -1, v0
	v_max_i32_e32 v240, -2, v0
	v_max_i32_e32 v241, -3, v0
	v_max_i32_e32 v242, -16, v0
	v_lshl_add_u32 v194, v188, 2, s13
	v_max_i32_e32 v0, 0xffffffed, v0
	v_lshl_add_u32 v3, v3, 2, s13
	v_lshl_add_u32 v240, v240, 2, s13
	v_lshl_add_u32 v241, v241, 2, s13
	v_lshl_add_u32 v242, v242, 2, s13
	v_lshl_add_u32 v0, v0, 2, s13
	ds_read_b32 v188, v2
	ds_read_b32 v189, v3 offset:4
	ds_read_b32 v190, v240 offset:8
	ds_read_b32 v191, v241 offset:12
	ds_read_b32 v192, v242 offset:64
	ds_read_b32 v193, v193 offset:68
	ds_read_b32 v194, v194 offset:72
	ds_read_b32 v195, v0 offset:76
	s_waitcnt lgkmcnt(4)
	v_mfma_f32_16x16x32_bf16 v[188:191], v[172:175], v[92:95], v[188:191]
	s_mov_b64 s[76:77], 0
	s_waitcnt lgkmcnt(0)
	v_mfma_f32_16x16x32_bf16 v[192:195], v[180:183], v[92:95], v[192:195]
	s_nop 0
	v_mfma_f32_16x16x32_bf16 v[188:191], v[176:179], v[96:99], v[188:191]
	v_mfma_f32_16x16x32_bf16 v[192:195], v[184:187], v[96:99], v[192:195]

.LBB0_511:
	s_cmp_lt_u32 s14, 6
	s_mov_b64 s[4:5], -1
	s_cbranch_scc1 .LBB0_513
	v_lshl_add_u32 v0, s14, 6, v234
	v_max_i32_e32 v188, 0xffffffef, v0
	v_max_i32_e32 v2, 0, v0
	v_lshl_add_u32 v193, v188, 2, s13
	v_max_i32_e32 v188, 0xffffffee, v0
	v_lshl_add_u32 v2, v2, 2, s13
	v_max_i32_e32 v3, -1, v0
	v_max_i32_e32 v240, -2, v0
	v_max_i32_e32 v241, -3, v0
	v_max_i32_e32 v242, -16, v0
	v_lshl_add_u32 v194, v188, 2, s13
	v_max_i32_e32 v0, 0xffffffed, v0
	v_lshl_add_u32 v3, v3, 2, s13
	v_lshl_add_u32 v240, v240, 2, s13
	v_lshl_add_u32 v241, v241, 2, s13
	v_lshl_add_u32 v242, v242, 2, s13
	v_lshl_add_u32 v0, v0, 2, s13
	ds_read_b32 v188, v2
	ds_read_b32 v189, v3 offset:4
	ds_read_b32 v190, v240 offset:8
	ds_read_b32 v191, v241 offset:12
	ds_read_b32 v192, v242 offset:64
	ds_read_b32 v193, v193 offset:68
	ds_read_b32 v194, v194 offset:72
	ds_read_b32 v195, v0 offset:76
	s_waitcnt lgkmcnt(4)
	v_mfma_f32_16x16x32_bf16 v[188:191], v[172:175], v[64:67], v[188:191]
	s_mov_b64 s[4:5], 0
	s_waitcnt lgkmcnt(0)
	v_mfma_f32_16x16x32_bf16 v[192:195], v[180:183], v[64:67], v[192:195]
	s_nop 0
	v_mfma_f32_16x16x32_bf16 v[188:191], v[176:179], v[68:71], v[188:191]
	v_mfma_f32_16x16x32_bf16 v[192:195], v[184:187], v[68:71], v[192:195]

.LBB0_515:
	s_nop 7
	v_exp_f32_e32 v2, v192
	v_exp_f32_e32 v240, v193
	v_exp_f32_e32 v241, v190
	v_exp_f32_e32 v242, v191
	v_exp_f32_e32 v0, v188
	v_exp_f32_e32 v3, v189
	v_exp_f32_e32 v191, v194
	v_exp_f32_e32 v192, v195
	v_cvt_pk_bf16_f32 v189, v241, v242
	v_cvt_pk_bf16_f32 v190, v2, v240
	v_cvt_pk_bf16_f32 v188, v0, v3
	v_cvt_pk_bf16_f32 v191, v191, v192
	s_waitcnt lgkmcnt(3)
	s_nop 0
	v_mfma_f32_16x16x32_bf16 v[120:123], v[160:163], v[188:191], v[120:123]
	s_waitcnt lgkmcnt(2)
	v_mfma_f32_16x16x32_bf16 v[108:111], v[156:159], v[188:191], v[108:111]
	s_waitcnt lgkmcnt(1)
	v_mfma_f32_16x16x32_bf16 v[104:107], v[164:167], v[188:191], v[104:107]
	s_waitcnt lgkmcnt(0)
	v_mfma_f32_16x16x32_bf16 v[100:103], v[168:171], v[188:191], v[100:103]
	v_mfma_f32_16x16x32_bf16 v[136:139], v[4:7], v[188:191], v[136:139]
	s_andn2_b64 vcc, exec, s[70:71]
	s_cbranch_vccnz .LBB0_508
.LBB0_516:
	s_cmp_lt_u32 s15, 6
	s_mov_b64 s[4:5], -1
	s_cbranch_scc1 .LBB0_518
	v_lshl_add_u32 v0, s15, 6, v234
	v_max_i32_e32 v188, 0xffffffef, v0
	v_max_i32_e32 v2, 0, v0
	v_lshl_add_u32 v193, v188, 2, s13
	v_max_i32_e32 v188, 0xffffffee, v0
	v_lshl_add_u32 v2, v2, 2, s13
	v_max_i32_e32 v3, -1, v0
	v_max_i32_e32 v240, -2, v0
	v_max_i32_e32 v241, -3, v0
	v_max_i32_e32 v242, -16, v0
	v_lshl_add_u32 v194, v188, 2, s13
	v_max_i32_e32 v0, 0xffffffed, v0
	v_lshl_add_u32 v3, v3, 2, s13
	v_lshl_add_u32 v240, v240, 2, s13
	v_lshl_add_u32 v241, v241, 2, s13
	v_lshl_add_u32 v242, v242, 2, s13
	v_lshl_add_u32 v0, v0, 2, s13
	ds_read_b32 v188, v2
	ds_read_b32 v189, v3 offset:4
	ds_read_b32 v190, v240 offset:8
	ds_read_b32 v191, v241 offset:12
	ds_read_b32 v192, v242 offset:64
	ds_read_b32 v193, v193 offset:68
	ds_read_b32 v194, v194 offset:72
	ds_read_b32 v195, v0 offset:76
	s_waitcnt lgkmcnt(4)
	v_mfma_f32_16x16x32_bf16 v[188:191], v[172:175], v[76:79], v[188:191]
	s_mov_b64 s[4:5], 0
	s_waitcnt lgkmcnt(0)
	v_mfma_f32_16x16x32_bf16 v[192:195], v[180:183], v[76:79], v[192:195]
	s_nop 0
	v_mfma_f32_16x16x32_bf16 v[188:191], v[176:179], v[80:83], v[188:191]
	v_mfma_f32_16x16x32_bf16 v[192:195], v[184:187], v[80:83], v[192:195]

.LBB0_521:
	s_cmp_lt_u32 s17, 6
	s_mov_b64 s[4:5], -1
	s_cbranch_scc1 .LBB0_523
	v_lshl_add_u32 v0, s17, 6, v234
	v_max_i32_e32 v188, 0xffffffef, v0
	v_max_i32_e32 v2, 0, v0
	v_lshl_add_u32 v193, v188, 2, s13
	v_max_i32_e32 v188, 0xffffffee, v0
	v_lshl_add_u32 v2, v2, 2, s13
	v_max_i32_e32 v3, -1, v0
	v_max_i32_e32 v240, -2, v0
	v_max_i32_e32 v241, -3, v0
	v_max_i32_e32 v242, -16, v0
	v_lshl_add_u32 v194, v188, 2, s13
	v_max_i32_e32 v0, 0xffffffed, v0
	v_lshl_add_u32 v3, v3, 2, s13
	v_lshl_add_u32 v240, v240, 2, s13
	v_lshl_add_u32 v241, v241, 2, s13
	v_lshl_add_u32 v242, v242, 2, s13
	v_lshl_add_u32 v0, v0, 2, s13
	ds_read_b32 v188, v2
	ds_read_b32 v189, v3 offset:4
	ds_read_b32 v190, v240 offset:8
	ds_read_b32 v191, v241 offset:12
	ds_read_b32 v192, v242 offset:64
	ds_read_b32 v193, v193 offset:68
	ds_read_b32 v194, v194 offset:72
	ds_read_b32 v195, v0 offset:76
	s_waitcnt lgkmcnt(4)
	v_mfma_f32_16x16x32_bf16 v[188:191], v[172:175], v[84:87], v[188:191]
	s_mov_b64 s[4:5], 0
	s_waitcnt lgkmcnt(0)
	v_mfma_f32_16x16x32_bf16 v[192:195], v[180:183], v[84:87], v[192:195]
	s_nop 0
	v_mfma_f32_16x16x32_bf16 v[188:191], v[176:179], v[88:91], v[188:191]
	v_mfma_f32_16x16x32_bf16 v[192:195], v[184:187], v[88:91], v[192:195]

.LBB0_526:
	s_cmp_lt_u32 s20, 6
	s_mov_b64 s[4:5], -1
	s_cbranch_scc1 .LBB0_528
	v_lshl_add_u32 v0, s20, 6, v234
	v_max_i32_e32 v188, 0xffffffef, v0
	v_max_i32_e32 v2, 0, v0
	v_lshl_add_u32 v193, v188, 2, s13
	v_max_i32_e32 v188, 0xffffffee, v0
	v_lshl_add_u32 v2, v2, 2, s13
	v_max_i32_e32 v3, -1, v0
	v_max_i32_e32 v240, -2, v0
	v_max_i32_e32 v241, -3, v0
	v_max_i32_e32 v242, -16, v0
	v_lshl_add_u32 v194, v188, 2, s13
	v_max_i32_e32 v0, 0xffffffed, v0
	v_lshl_add_u32 v3, v3, 2, s13
	v_lshl_add_u32 v240, v240, 2, s13
	v_lshl_add_u32 v241, v241, 2, s13
	v_lshl_add_u32 v242, v242, 2, s13
	v_lshl_add_u32 v0, v0, 2, s13
	ds_read_b32 v188, v2
	ds_read_b32 v189, v3 offset:4
	ds_read_b32 v190, v240 offset:8
	ds_read_b32 v191, v241 offset:12
	ds_read_b32 v192, v242 offset:64
	ds_read_b32 v193, v193 offset:68
	ds_read_b32 v194, v194 offset:72
	ds_read_b32 v195, v0 offset:76
	s_waitcnt lgkmcnt(4)
	v_mfma_f32_16x16x32_bf16 v[188:191], v[172:175], v[92:95], v[188:191]
	s_mov_b64 s[4:5], 0
	s_waitcnt lgkmcnt(0)
	v_mfma_f32_16x16x32_bf16 v[192:195], v[180:183], v[92:95], v[192:195]
	s_nop 0
	v_mfma_f32_16x16x32_bf16 v[188:191], v[176:179], v[96:99], v[188:191]
	v_mfma_f32_16x16x32_bf16 v[192:195], v[184:187], v[96:99], v[192:195]

.LBB0_530:
	s_nop 7
	v_exp_f32_e32 v2, v192
	v_exp_f32_e32 v240, v193
	v_exp_f32_e32 v241, v190
	v_exp_f32_e32 v242, v191
	v_exp_f32_e32 v0, v188
	v_exp_f32_e32 v3, v189
	v_exp_f32_e32 v155, v194
	s_waitcnt lgkmcnt(11)
	v_exp_f32_e32 v172, v195
	v_cvt_pk_bf16_f32 v153, v241, v242
	v_cvt_pk_bf16_f32 v154, v2, v240
	v_cvt_pk_bf16_f32 v152, v0, v3
	v_cvt_pk_bf16_f32 v155, v155, v172
	s_waitcnt lgkmcnt(3)
	s_nop 0
	v_mfma_f32_16x16x32_bf16 v[20:23], v[160:163], v[152:155], v[20:23]
	s_waitcnt lgkmcnt(2)
	v_mfma_f32_16x16x32_bf16 v[16:19], v[156:159], v[152:155], v[16:19]
	s_waitcnt lgkmcnt(1)
	v_mfma_f32_16x16x32_bf16 v[12:15], v[164:167], v[152:155], v[12:15]
	s_waitcnt lgkmcnt(0)
	v_mfma_f32_16x16x32_bf16 v[8:11], v[168:171], v[152:155], v[8:11]
	v_mfma_f32_16x16x32_bf16 v[24:27], v[4:7], v[152:155], v[24:27]
	s_andn2_b64 vcc, exec, s[66:67]
	s_mov_b64 s[4:5], -1
	s_cbranch_vccnz .LBB0_330
